# plus: static priority raise for waves 4-7 inside the scan loop; prep loop: invariant a_log/dt_bias/conv-weight loads hoisted, next-item prefetch and stores no longer drained mid-item
# speedup vs baseline: 1.2058x; 1.0024x over previous
.LBB0_515:
	s_lshl_b32 s9, s97, 3
	v_mbcnt_lo_u32_b32 v2, -1, 0
	v_mbcnt_hi_u32_b32 v2, -1, v2
	s_lshl_b32 s24, s2, 3
	s_mov_b32 s25, 0xbfb8aa3b
	s_mov_b32 s33, 0x42ce8ed0
	s_mov_b32 s7, 0
	s_mov_b32 s36, 0xc2b17218
	v_mov_b32_e32 v97, 0x7f800000
	v_mov_b32_e32 v98, 0x3ecc95a3
	v_and_b32_e32 v99, 64, v2
	v_mov_b32_e32 v59, 0
	s_mov_b32 s8, 0x3db504f3
	s_movk_i32 s37, 0x110
	s_add_i32 s38, 0, 0x11800
	s_add_i32 s39, 0, 0x15800
	s_add_i32 s40, 0, 0x19c00
	s_movk_i32 s41, 0x90
	s_add_i32 s42, 0, 0x1e000
	v_mov_b32_e32 v100, 0x1800
	v_mov_b32_e32 v101, 0x3fb8aa3b
	v_mov_b32_e32 v102, 0x358637bd
	v_mov_b32_e32 v103, 0x32a5705f
	v_mov_b32_e32 v104, 0xc2ce8ed0
	v_mov_b32_e32 v105, 0x42b17218
	s_waitcnt vmcnt(24)
	v_mov_b32_e32 v56, v33
	v_mov_b32_e32 v55, v37
	s_waitcnt vmcnt(23)
	v_mov_b32_e32 v54, v39
	s_bfe_u32 s98, s2, 0x30005
	s_lshl_b32 s99, s98, 2
	v_mov_b32_e32 v216, s99
	v_readlane_b32 s100, v245, 30
	v_readlane_b32 s101, v245, 31
	s_nop 4
	global_load_dword v190, v216, s[100:101]
	v_readlane_b32 s100, v245, 32
	v_readlane_b32 s101, v245, 33
	s_nop 4
	global_load_dword v191, v216, s[100:101]
	v_and_b32_e32 v216, 63, v0
	v_lshlrev_b32_e32 v217, 1, v216
	v_lshlrev_b32_e32 v218, 3, v216
	v_and_b32_e32 v218, 16, v218
	v_and_b32_e32 v219, 12, v216
	v_and_b32_e32 v217, 0x62, v217
	v_or3_b32 v217, v218, v219, v217
	s_lshl_b32 s99, s98, 7
	v_or_b32_e32 v217, s99, v217
	v_lshlrev_b32_e32 v217, 2, v217
	v_readlane_b32 s100, v245, 28
	v_readlane_b32 s101, v245, 29
	s_nop 4
	global_load_dwordx2 v[192:193], v217, s[100:101]
	s_add_u32 s100, s100, 0x1000
	s_addc_u32 s101, s101, 0
	global_load_dwordx2 v[194:195], v217, s[100:101]
	s_add_u32 s100, s100, 0x1000
	s_addc_u32 s101, s101, 0
	global_load_dwordx2 v[196:197], v217, s[100:101]
	s_add_u32 s100, s100, 0x1000
	s_addc_u32 s101, s101, 0
	global_load_dwordx2 v[198:199], v217, s[100:101]
	s_add_u32 s100, s100, 0x1000
	s_addc_u32 s101, s101, 0
	global_load_dwordx2 v[200:201], v217, s[100:101]
	s_add_u32 s100, s100, 0x1000
	s_addc_u32 s101, s101, 0
	global_load_dwordx2 v[202:203], v217, s[100:101]
	s_add_u32 s100, s100, 0x1000
	s_addc_u32 s101, s101, 0
	global_load_dwordx2 v[204:205], v217, s[100:101]
	s_add_u32 s100, s100, 0x1000
	s_addc_u32 s101, s101, 0
	global_load_dwordx2 v[206:207], v217, s[100:101]
	s_add_u32 s100, s100, 0x1000
	s_addc_u32 s101, s101, 0
	global_load_dwordx2 v[208:209], v217, s[100:101]
	s_add_u32 s100, s100, 0x1000
	s_addc_u32 s101, s101, 0
	global_load_dwordx2 v[210:211], v217, s[100:101]
	s_add_u32 s100, s100, 0x1000
	s_addc_u32 s101, s101, 0
	global_load_dwordx2 v[212:213], v217, s[100:101]
	s_add_u32 s100, s100, 0x1000
	s_addc_u32 s101, s101, 0
	global_load_dwordx2 v[214:215], v217, s[100:101]
	s_waitcnt vmcnt(0)
	s_branch .LBB0_517
.LBB0_516:
	s_or_b64 exec, exec, s[4:5]
	s_waitcnt vmcnt(21)
	s_add_i32 s24, s24, s9
	s_and_b64 vcc, exec, s[10:11]
	s_mov_b32 s2, s43
	v_mov_b32_e32 v148, v142
	v_mov_b32_e32 v146, v137
	v_mov_b32_e32 v49, v133
	v_mov_b32_e32 v46, v131
	v_mov_b32_e32 v45, v129
	v_mov_b32_e32 v44, v125
	v_mov_b32_e32 v43, v122
	v_mov_b32_e32 v42, v120
	v_mov_b32_e32 v36, v115
	v_mov_b32_e32 v34, v113
	v_mov_b32_e32 v31, v108
	v_mov_b32_e32 v152, v143
	v_mov_b32_e32 v151, v138
	v_mov_b32_e32 v149, v135
	v_mov_b32_e32 v145, v132
	v_mov_b32_e32 v53, v130
	v_mov_b32_e32 v52, v126
	v_mov_b32_e32 v51, v123
	v_mov_b32_e32 v47, v121
	v_mov_b32_e32 v38, v114
	v_mov_b32_e32 v35, v111
	v_mov_b32_e32 v32, v110
	v_mov_b32_e32 v30, v109
	v_mov_b32_e32 v33, v112
	v_mov_b32_e32 v56, v112
	v_mov_b32_e32 v37, v116
	v_mov_b32_e32 v55, v116
	v_mov_b32_e32 v39, v117
	v_mov_b32_e32 v54, v117
	v_mov_b32_e32 v41, v118
	v_mov_b32_e32 v40, v119
	v_mov_b32_e32 v50, v124
	v_mov_b32_e32 v48, v127
	v_mov_b32_e32 v144, v128
	v_mov_b32_e32 v147, v134
	v_mov_b32_e32 v150, v136
	s_cbranch_vccnz .LBB0_623
.LBB0_517:
	s_bfe_u32 s46, s2, 0x30005
	v_mov_b32_e32 v106, v0
	s_lshl_b32 s4, s46, 2
	v_readlane_b32 s48, v245, 26
	s_waitcnt lgkmcnt(0)
	s_barrier
	v_mov_b32_e32 v2, s4
	v_readlane_b32 s52, v245, 30
	v_readlane_b32 s53, v245, 31
	v_readlane_b32 s54, v245, 32
	v_readlane_b32 s55, v245, 33
	s_nop 2
	v_mov_b32_e32 v5, v190
	s_nop 0
	v_mov_b32_e32 v6, v191
	v_add_u32_e32 v7, -1, v106
	v_and_or_b32 v7, v7, 63, v99
	v_lshlrev_b32_e32 v8, 2, v7
	s_mov_b32 s4, 0x3fb8aa3b
	v_and_b32_e32 v107, 63, v106
	v_mul_f32_e32 v4, 0xbfb8aa3b, v1
	v_rndne_f32_e32 v3, v4
	v_fma_f32 v2, v1, s25, -v4
	v_sub_f32_e32 v4, v4, v3
	v_fmac_f32_e32 v2, 0xb2a5705f, v1
	v_add_f32_e32 v2, v4, v2
	v_cvt_i32_f32_e32 v3, v3
	v_exp_f32_e32 v2, v2
	v_readfirstlane_b32 s45, v0
	s_cmp_lt_u32 s45, 64
	s_cselect_b64 s[12:13], -1, 0
	v_ldexp_f32 v2, v2, v3
	s_cmp_gt_u32 s45, 63
	v_readlane_b32 s49, v245, 27
	v_readlane_b32 s50, v245, 28
	v_readlane_b32 s51, v245, 29
	v_readlane_b32 s56, v245, 34
	v_readlane_b32 s57, v245, 35
	v_readlane_b32 s58, v245, 36
	v_readlane_b32 s59, v245, 37
	v_readlane_b32 s60, v245, 38
	v_readlane_b32 s61, v245, 39
	v_readlane_b32 s62, v245, 40
	v_readlane_b32 s63, v245, 41
	s_nop 0
	v_mul_f32_e32 v7, 0x3fb8aa3b, v5
	s_nop 0
	v_add_f32_e32 v6, v96, v6
	v_fma_f32 v9, v5, s4, -v7
	v_rndne_f32_e32 v10, v7
	v_mul_f32_e64 v12, |v6|, s25
	v_fmac_f32_e32 v9, 0x32a5705f, v5
	v_sub_f32_e32 v7, v7, v10
	v_fma_f32 v13, |v6|, s25, -v12
	v_rndne_f32_e32 v14, v12
	v_add_f32_e32 v7, v7, v9
	s_mov_b32 s4, 0xb2a5705f
	v_cvt_i32_f32_e32 v10, v10
	v_fma_f32 v9, |v6|, s4, v13
	v_sub_f32_e32 v12, v12, v14
	v_exp_f32_e32 v7, v7
	v_add_f32_e32 v9, v12, v9
	v_cvt_i32_f32_e32 v13, v14
	v_exp_f32_e32 v9, v9
	s_mov_b32 s4, 0xc2ce8ed0
	v_ldexp_f32 v7, v7, v10
	v_cmp_ngt_f32_e32 vcc, s4, v5
	s_mov_b32 s4, 0x42b17218
	v_ldexp_f32 v9, v9, v13
	v_cndmask_b32_e32 v7, 0, v7, vcc
	v_cmp_nlt_f32_e32 vcc, s4, v5
	v_max_f32_e32 v11, 0, v6
	s_mov_b32 s4, 0x3f2aaaab
	v_cndmask_b32_e32 v5, v97, v7, vcc
	v_cmp_ngt_f32_e64 vcc, |v6|, s33
	s_nop 1
	v_cndmask_b32_e32 v7, 0, v9, vcc
	v_cmp_nlt_f32_e64 vcc, |v6|, s36
	s_nop 1
	v_cndmask_b32_e32 v9, v97, v7, vcc
	v_add_f32_e32 v10, 1.0, v9
	v_add_f32_e32 v12, -1.0, v10
	v_frexp_mant_f32_e32 v13, v10
	v_cvt_f64_f32_e32 v[6:7], v10
	v_sub_f32_e32 v14, v12, v10
	v_frexp_exp_i32_f64_e32 v6, v[6:7]
	v_cmp_gt_f32_e32 vcc, s4, v13
	v_sub_f32_e32 v12, v9, v12
	v_add_f32_e32 v7, 1.0, v14
	v_subbrev_co_u32_e32 v6, vcc, 0, v6, vcc
	v_add_f32_e32 v7, v12, v7
	v_sub_u32_e32 v12, 0, v6
	v_cvt_f32_i32_e32 v6, v6
	v_ldexp_f32 v10, v10, v12
	v_ldexp_f32 v7, v7, v12
	v_add_f32_e32 v12, -1.0, v10
	v_add_f32_e32 v13, 1.0, v10
	v_add_f32_e32 v14, 1.0, v12
	v_add_f32_e32 v15, -1.0, v13
	v_sub_f32_e32 v14, v10, v14
	v_sub_f32_e32 v10, v10, v15
	v_mul_f32_e32 v15, 0x3f317218, v6
	v_add_f32_e32 v14, v7, v14
	v_add_f32_e32 v7, v7, v10
	s_mov_b32 s4, 0x3f317218
	v_fma_f32 v10, v6, s4, -v15
	v_add_f32_e32 v16, v12, v14
	v_add_f32_e32 v17, v13, v7
	v_fmac_f32_e32 v10, 0xb102e308, v6
	v_sub_f32_e32 v6, v12, v16
	v_sub_f32_e32 v12, v13, v17
	v_rcp_f32_e32 v13, v17
	v_add_f32_e32 v18, v15, v10
	v_add_f32_e32 v7, v7, v12
	v_sub_f32_e32 v12, v18, v15
	v_sub_f32_e32 v10, v10, v12
	v_mul_f32_e32 v12, v16, v13
	v_add_f32_e32 v6, v14, v6
	v_mul_f32_e32 v14, v17, v12
	v_fma_f32 v15, v12, v17, -v14
	v_fmac_f32_e32 v15, v12, v7
	v_add_f32_e32 v19, v14, v15
	v_sub_f32_e32 v20, v16, v19
	v_sub_f32_e32 v14, v19, v14
	v_sub_f32_e32 v16, v16, v20
	v_sub_f32_e32 v14, v14, v15
	v_sub_f32_e32 v15, v16, v19
	v_add_f32_e32 v6, v6, v15
	v_add_f32_e32 v6, v14, v6
	v_add_f32_e32 v14, v20, v6
	v_mul_f32_e32 v15, v13, v14
	v_sub_f32_e32 v16, v20, v14
	v_mul_f32_e32 v19, v17, v15
	v_add_f32_e32 v6, v6, v16
	v_add_f32_e32 v16, v12, v15
	v_fma_f32 v17, v15, v17, -v19
	v_sub_f32_e32 v12, v16, v12
	v_fmac_f32_e32 v17, v15, v7
	v_sub_f32_e32 v7, v15, v12
	v_add_f32_e32 v12, v19, v17
	v_sub_f32_e32 v15, v12, v19
	v_sub_f32_e32 v19, v14, v12
	v_sub_f32_e32 v14, v14, v19
	v_sub_f32_e32 v12, v14, v12
	v_sub_f32_e32 v15, v15, v17
	v_add_f32_e32 v6, v6, v12
	v_add_f32_e32 v6, v15, v6
	v_add_f32_e32 v6, v19, v6
	v_mul_f32_e32 v6, v13, v6
	v_add_f32_e32 v6, v7, v6
	v_add_f32_e32 v7, v16, v6
	v_mul_f32_e32 v12, v7, v7
	v_fmamk_f32 v15, v12, 0x3e9b6dac, v98
	v_sub_f32_e32 v13, v7, v16
	v_ldexp_f32 v14, v7, 1
	v_mul_f32_e32 v7, v7, v12
	v_fmaak_f32 v12, v12, v15, 0x3f2aaada
	v_mul_f32_e32 v7, v7, v12
	v_add_f32_e32 v12, v14, v7
	v_sub_f32_e32 v6, v6, v13
	v_sub_f32_e32 v13, v12, v14
	v_ldexp_f32 v6, v6, 1
	v_sub_f32_e32 v7, v7, v13
	v_add_f32_e32 v6, v6, v7
	v_add_f32_e32 v7, v12, v6
	v_sub_f32_e32 v12, v7, v12
	v_add_f32_e32 v13, v18, v7
	v_sub_f32_e32 v6, v6, v12
	v_sub_f32_e32 v12, v13, v18
	v_sub_f32_e32 v14, v13, v12
	v_sub_f32_e32 v7, v7, v12
	v_add_f32_e32 v12, v10, v6
	v_sub_f32_e32 v14, v18, v14
	v_sub_f32_e32 v15, v12, v10
	v_add_f32_e32 v7, v7, v14
	v_sub_f32_e32 v14, v12, v15
	v_sub_f32_e32 v6, v6, v15
	v_sub_f32_e32 v10, v10, v14
	v_add_f32_e32 v7, v12, v7
	v_add_f32_e32 v6, v6, v10
	v_add_f32_e32 v10, v13, v7
	v_sub_f32_e32 v12, v10, v13
	v_sub_f32_e32 v7, v7, v12
	v_add_f32_e32 v6, v6, v7
	s_mov_b32 s4, 0x7f800000
	v_add_f32_e32 v6, v10, v6
	v_cmp_neq_f32_e32 vcc, s4, v9
	s_mov_b32 s4, 0x33800000
	s_nop 0
	v_cndmask_b32_e32 v6, v97, v6, vcc
	v_cmp_lt_f32_e64 vcc, |v9|, s4
	s_nop 1
	v_cndmask_b32_e32 v6, v6, v9, vcc
	v_add_f32_e32 v6, v11, v6
	v_mul_f32_e64 v7, v6, -v5
	ds_bpermute_b32 v8, v8, v7
	v_add_u32_e32 v9, 62, v106
	v_and_or_b32 v9, v9, 63, v99
	v_cmp_eq_u32_e32 vcc, 0, v107
	v_lshlrev_b32_e32 v9, 2, v9
	s_waitcnt lgkmcnt(0)
	v_fma_f32 v5, v6, -v5, v8
	v_cndmask_b32_e32 v5, v5, v7, vcc
	ds_bpermute_b32 v6, v9, v5
	v_add_u32_e32 v7, 60, v106
	v_and_or_b32 v7, v7, 63, v99
	v_cmp_gt_u32_e32 vcc, 2, v107
	v_lshlrev_b32_e32 v7, 2, v7
	s_waitcnt lgkmcnt(0)
	v_add_f32_e32 v6, v5, v6
	v_cndmask_b32_e32 v5, v6, v5, vcc
	ds_bpermute_b32 v6, v7, v5
	v_add_u32_e32 v7, 56, v106
	v_cmp_gt_u32_e32 vcc, 4, v107
	s_waitcnt lgkmcnt(0)
	v_add_f32_e32 v4, v5, v6
	v_cndmask_b32_e32 v4, v4, v5, vcc
	v_and_or_b32 v5, v7, 63, v99
	v_lshlrev_b32_e32 v5, 2, v5
	ds_bpermute_b32 v5, v5, v4
	v_cmp_gt_u32_e32 vcc, 8, v107
	s_waitcnt lgkmcnt(0)
	v_add_f32_e32 v3, v4, v5
	v_cndmask_b32_e32 v3, v3, v4, vcc
	v_add_u32_e32 v4, 48, v106
	v_and_or_b32 v4, v4, 63, v99
	v_lshlrev_b32_e32 v4, 2, v4
	ds_bpermute_b32 v4, v4, v3
	v_cmp_nlt_f32_e32 vcc, s33, v1
	s_waitcnt lgkmcnt(0)
	v_add_f32_e32 v4, v3, v4
	v_cndmask_b32_e32 v2, 0, v2, vcc
	v_cmp_ngt_f32_e32 vcc, s36, v1
	s_nop 1
	v_cndmask_b32_e32 v2, v97, v2, vcc
	v_cmp_gt_u32_e32 vcc, 16, v107
	v_add_f32_e32 v2, 1.0, v2
	v_div_scale_f32 v5, s[4:5], v2, v2, 1.0
	v_cndmask_b32_e32 v3, v4, v3, vcc
	v_or_b32_e32 v4, v99, v107
	v_lshlrev_b32_e32 v4, 2, v4
	v_xor_b32_e32 v4, 0x80, v4
	ds_bpermute_b32 v4, v4, v3
	v_rcp_f32_e32 v6, v5
	v_cmp_gt_u32_e32 vcc, 32, v107
	s_waitcnt lgkmcnt(0)
	v_add_f32_e32 v4, v3, v4
	v_cndmask_b32_e32 v153, v4, v3, vcc
	v_fma_f32 v3, -v5, v6, 1.0
	v_fmac_f32_e32 v6, v3, v6
	v_div_scale_f32 v3, vcc, 1.0, v2, 1.0
	v_mul_f32_e32 v4, v3, v6
	v_fma_f32 v7, -v5, v4, v3
	v_fmac_f32_e32 v4, v7, v6
	v_fma_f32 v3, -v5, v4, v3
	v_div_fmas_f32 v3, v3, v6, v4
	v_div_fixup_f32 v154, v3, v2, 1.0
	s_cbranch_scc1 .LBB0_519
	v_lshl_add_u32 v2, v107, 2, 0
	v_add_u32_e32 v3, 0x20400, v2
	v_add_u32_e32 v2, 0x20500, v2
	ds_write_b32 v3, v153
	ds_write_b32 v2, v154
.LBB0_519:
	s_add_i32 s43, s2, s97
	v_lshlrev_b32_e32 v156, 1, v107
	v_lshlrev_b32_e32 v2, 3, v107
	s_cmpk_gt_i32 s43, 0x7ff
	v_and_b32_e32 v2, 16, v2
	v_and_b32_e32 v3, 12, v106
	v_and_b32_e32 v4, 0x62, v156
	s_cselect_b64 s[10:11], -1, 0
	v_or3_b32 v155, v2, v3, v4
	s_lshl_b32 s47, s46, 7
	v_or_b32_e32 v2, s47, v155
	v_readlane_b32 s48, v245, 26
	v_lshlrev_b32_e32 v58, 2, v2
	v_readlane_b32 s50, v245, 28
	v_readlane_b32 s51, v245, 29
	v_readlane_b32 s44, v153, 63
	v_mov_b32_e32 v136, v150
	v_lshl_add_u64 v[12:13], s[50:51], 0, v[58:59]
	v_add_co_u32_e32 v2, vcc, 0x2000, v12
	v_mov_b32_e32 v134, v147
	s_nop 0
	v_addc_co_u32_e32 v3, vcc, 0, v13, vcc
	v_add_co_u32_e32 v4, vcc, 0x5000, v12
	v_mov_b32_e32 v128, v144
	s_nop 0
	v_addc_co_u32_e32 v5, vcc, 0, v13, vcc
	v_add_co_u32_e32 v8, vcc, 0x8000, v12
	v_mov_b32_e32 v127, v48
	s_nop 0
	v_addc_co_u32_e32 v9, vcc, 0, v13, vcc
	v_add_co_u32_e32 v10, vcc, 0xb000, v12
	v_mov_b32_e32 v124, v50
	s_nop 0
	v_addc_co_u32_e32 v11, vcc, 0, v13, vcc
	v_mov_b64_e32 v[2:3], v[196:197]
	s_nop 0
	v_mov_b64_e32 v[6:7], v[202:203]
	s_nop 0
	v_mov_b64_e32 v[4:5], v[208:209]
	s_nop 0
	v_mov_b64_e32 v[8:9], v[214:215]
	v_add_co_u32_e32 v10, vcc, 0x3000, v12
	v_mov_b32_e32 v119, v40
	s_nop 0
	v_addc_co_u32_e32 v11, vcc, 0, v13, vcc
	v_add_co_u32_e32 v14, vcc, 0x6000, v12
	v_mov_b32_e32 v118, v41
	s_nop 0
	v_addc_co_u32_e32 v15, vcc, 0, v13, vcc
	v_add_co_u32_e32 v16, vcc, 0x9000, v12
	v_mov_b32_e32 v117, v54
	s_nop 0
	v_addc_co_u32_e32 v17, vcc, 0, v13, vcc
	v_add_co_u32_e32 v24, vcc, 0x1000, v12
	v_mov_b32_e32 v139, v39
	s_nop 0
	v_addc_co_u32_e32 v25, vcc, 0, v13, vcc
	v_mov_b64_e32 v[22:23], v[198:199]
	v_mov_b64_e32 v[18:19], v[204:205]
	v_mov_b64_e32 v[20:21], v[210:211]
	s_nop 0
	v_mov_b64_e32 v[10:11], v[194:195]
	v_add_co_u32_e32 v14, vcc, 0x4000, v12
	v_mov_b32_e32 v116, v55
	s_nop 0
	v_addc_co_u32_e32 v15, vcc, 0, v13, vcc
	v_add_co_u32_e32 v16, vcc, 0x7000, v12
	v_mov_b32_e32 v140, v37
	s_nop 0
	v_addc_co_u32_e32 v17, vcc, 0, v13, vcc
	v_add_co_u32_e32 v26, vcc, 0xa000, v12
	v_mov_b32_e32 v112, v56
	s_nop 0
	v_addc_co_u32_e32 v27, vcc, 0, v13, vcc
	v_mov_b64_e32 v[24:25], v[192:193]
	s_nop 0
	v_mov_b64_e32 v[14:15], v[200:201]
	s_nop 0
	v_mov_b64_e32 v[12:13], v[206:207]
	s_nop 0
	v_mov_b64_e32 v[16:17], v[212:213]
	s_and_b64 vcc, exec, s[10:11]
	v_mov_b32_e32 v141, v33
	v_mov_b32_e32 v109, v30
	v_mov_b32_e32 v142, v148
	v_mov_b32_e32 v137, v146
	v_mov_b32_e32 v133, v49
	v_mov_b32_e32 v131, v46
	v_mov_b32_e32 v129, v45
	v_mov_b32_e32 v125, v44
	v_mov_b32_e32 v122, v43
	v_mov_b32_e32 v120, v42
	v_mov_b32_e32 v115, v36
	v_mov_b32_e32 v113, v34
	v_mov_b32_e32 v108, v31
	v_mov_b32_e32 v143, v152
	v_mov_b32_e32 v138, v151
	v_mov_b32_e32 v135, v149
	v_mov_b32_e32 v132, v145
	v_mov_b32_e32 v130, v53
	v_mov_b32_e32 v126, v52
	v_mov_b32_e32 v123, v51
	v_mov_b32_e32 v121, v47
	v_mov_b32_e32 v114, v38
	v_mov_b32_e32 v111, v35
	v_mov_b32_e32 v110, v32
	v_readlane_b32 s49, v245, 27
	v_readlane_b32 s52, v245, 30
	v_readlane_b32 s53, v245, 31
	v_readlane_b32 s54, v245, 32
	v_readlane_b32 s55, v245, 33
	v_readlane_b32 s56, v245, 34
	v_readlane_b32 s57, v245, 35
	v_readlane_b32 s58, v245, 36
	v_readlane_b32 s59, v245, 37
	v_readlane_b32 s60, v245, 38
	v_readlane_b32 s61, v245, 39
	v_readlane_b32 s62, v245, 40
	v_readlane_b32 s63, v245, 41
	s_cbranch_vccnz .LBB0_541
	s_and_b32 s4, s43, 31
	s_add_i32 s5, s9, s24
	s_and_b32 s5, s5, 0xfffff800
	s_lshl_b32 s6, s4, 6
	v_mov_b32_e32 v26, v0
	s_or_b32 s48, s6, s5
	s_bfe_u32 s50, s43, 0x30005
	v_and_or_b32 v28, v26, 63, s48
	v_ashrrev_i32_e32 v29, 31, v28
	v_lshlrev_b64 v[28:29], 6, v[28:29]
	v_lshl_add_u64 v[28:29], s[86:87], 0, v[28:29]
	s_lshl_b32 s6, s50, 2
	v_lshl_add_u64 v[28:29], v[28:29], 0, s[6:7]
	global_load_dword v1, v[28:29], off
	global_load_dword v96, v[28:29], off offset:32
	v_readfirstlane_b32 s5, v0
	s_lshr_b32 s6, s5, 3
	s_and_b32 s49, s6, 0x1ffffff8
	s_cmp_lg_u32 s4, 0
	s_cselect_b64 s[4:5], -1, 0
	s_cmp_lg_u32 s49, 0
	s_cselect_b64 s[16:17], -1, 0
	s_cmp_eq_u32 s49, 0
	s_cbranch_scc1 .LBB0_522
	s_add_i32 s14, s48, s49
	s_add_i32 s18, s14, -3
	s_ashr_i32 s19, s18, 31
	s_mov_b64 s[22:23], 0
	s_mov_b64 s[20:21], -1
	s_branch .LBB0_523

.LBB0_540:
	s_add_i32 s14, s49, s48
	v_mad_i64_i32 v[28:29], s[4:5], s14, v100, v[26:27]
	v_add_co_u32_e32 v60, vcc, 0x1000, v28
	s_add_i32 s4, s14, 1
	s_nop 0
	v_addc_co_u32_e32 v61, vcc, 0, v29, vcc
	global_load_dword v117, v[60:61], off nt
	global_load_dword v120, v[28:29], off offset:2048 nt
	global_load_dword v121, v[28:29], off nt
	v_mad_i64_i32 v[28:29], s[4:5], s4, v100, v[26:27]
	v_add_co_u32_e32 v60, vcc, 0x1000, v28
	s_add_i32 s4, s14, 2
	s_nop 0
	v_addc_co_u32_e32 v61, vcc, 0, v29, vcc
	global_load_dword v118, v[60:61], off nt
	global_load_dword v122, v[28:29], off offset:2048 nt
	global_load_dword v123, v[28:29], off nt
	v_mad_i64_i32 v[28:29], s[4:5], s4, v100, v[26:27]
	v_add_co_u32_e32 v60, vcc, 0x1000, v28
	s_add_i32 s4, s14, 3
	s_nop 0
	v_addc_co_u32_e32 v61, vcc, 0, v29, vcc
	global_load_dword v119, v[60:61], off nt
	global_load_dword v125, v[28:29], off offset:2048 nt
	global_load_dword v126, v[28:29], off nt
	v_mad_i64_i32 v[28:29], s[4:5], s4, v100, v[26:27]
	v_add_co_u32_e32 v60, vcc, 0x1000, v28
	s_add_i32 s4, s14, 4
	s_nop 0
	v_addc_co_u32_e32 v61, vcc, 0, v29, vcc
	global_load_dword v124, v[60:61], off nt
	global_load_dword v129, v[28:29], off offset:2048 nt
	global_load_dword v130, v[28:29], off nt
	v_mad_i64_i32 v[28:29], s[4:5], s4, v100, v[26:27]
	v_add_co_u32_e32 v60, vcc, 0x1000, v28
	s_add_i32 s4, s14, 5
	s_nop 0
	v_addc_co_u32_e32 v61, vcc, 0, v29, vcc
	global_load_dword v127, v[60:61], off nt
	global_load_dword v131, v[28:29], off offset:2048 nt
	global_load_dword v132, v[28:29], off nt
	v_mad_i64_i32 v[28:29], s[4:5], s4, v100, v[26:27]
	v_add_co_u32_e32 v60, vcc, 0x1000, v28
	s_add_i32 s14, s14, 6
	s_nop 0
	v_addc_co_u32_e32 v61, vcc, 0, v29, vcc
	global_load_dword v128, v[60:61], off nt
	global_load_dword v133, v[28:29], off offset:2048 nt
	global_load_dword v135, v[28:29], off nt
	v_mad_i64_i32 v[28:29], s[4:5], s14, v100, v[26:27]
	s_or_b32 s4, s6, 7
	v_add_co_u32_e32 v60, vcc, 0x1000, v28
	s_add_i32 s4, s4, s48
	s_nop 0
	v_addc_co_u32_e32 v61, vcc, 0, v29, vcc
	v_mad_i64_i32 v[26:27], s[4:5], s4, v100, v[26:27]
	global_load_dword v134, v[60:61], off nt
	global_load_dword v137, v[28:29], off offset:2048 nt
	global_load_dword v138, v[28:29], off nt
	v_add_co_u32_e32 v28, vcc, 0x1000, v26
	v_addc_co_u32_e32 v29, vcc, 0, v27, vcc
	global_load_dword v136, v[28:29], off nt
	global_load_dword v142, v[26:27], off offset:2048 nt
	global_load_dword v143, v[26:27], off nt
.LBB0_541:
	v_lshlrev_b32_e32 v94, 16, v35
	v_and_b32_e32 v95, 0xffff0000, v35
	s_and_b32 s6, s2, 31
	v_lshlrev_b32_e32 v158, 16, v32
	v_and_b32_e32 v159, 0xffff0000, v32
	v_lshlrev_b32_e32 v70, 16, v56
	v_lshlrev_b32_e32 v75, 16, v41
	v_and_b32_e32 v79, 0xffff0000, v41
	v_lshlrev_b32_e32 v56, 16, v40
	v_and_b32_e32 v60, 0xffff0000, v40
	v_lshlrev_b32_e32 v40, 16, v146
	v_and_b32_e32 v41, 0xffff0000, v146
	v_lshlrev_b32_e32 v28, 16, v147
	v_and_b32_e32 v32, 0xffff0000, v147
	s_lshl_b32 s4, s6, 6
	s_lshr_b32 s20, s45, 6
	s_and_b32 s5, s24, 0xfffff800
	s_nop 0
	v_pk_mul_f32 v[146:147], v[22:23], v[94:95]
	v_lshlrev_b32_e32 v86, 16, v38
	v_and_b32_e32 v87, 0xffff0000, v38
	s_or_b32 s15, s4, s5
	s_lshl_b32 s16, s20, 3
	s_lshl_b32 s14, s47, 1
	s_nop 0
	v_pk_fma_f32 v[146:147], v[24:25], v[158:159], v[146:147]
	v_lshlrev_b32_e32 v82, 16, v47
	v_and_b32_e32 v83, 0xffff0000, v47
	s_add_u32 s4, s3, s14
	v_pk_fma_f32 v[146:147], v[18:19], v[86:87], v[146:147]
	v_lshlrev_b32_e32 v58, 1, v156
	s_addc_u32 s5, s85, 0
	v_pk_fma_f32 v[146:147], v[20:21], v[82:83], v[146:147]
	v_lshlrev_b32_e32 v71, 16, v37
	v_lshlrev_b32_e32 v84, 16, v36
	v_and_b32_e32 v85, 0xffff0000, v36
	v_lshlrev_b32_e32 v72, 16, v55
	v_lshlrev_b32_e32 v74, 16, v54
	v_and_b32_e32 v163, 0xffff0000, v37
	v_lshlrev_b32_e32 v64, 16, v52
	v_and_b32_e32 v65, 0xffff0000, v52
	v_lshlrev_b32_e32 v62, 16, v44
	v_and_b32_e32 v63, 0xffff0000, v44
	v_lshlrev_b32_e32 v54, 16, v53
	v_and_b32_e32 v55, 0xffff0000, v53
	v_lshlrev_b32_e32 v52, 16, v45
	v_and_b32_e32 v53, 0xffff0000, v45
	v_lshlrev_b32_e32 v44, 16, v145
	v_and_b32_e32 v45, 0xffff0000, v145
	v_add_u32_e32 v145, 0, v58
	v_lshl_add_u64 v[36:37], s[4:5], 0, v[58:59]
	v_mul_f32_e32 v58, 0xbfb8aa3b, v146
	v_lshlrev_b32_e32 v89, 16, v33
	v_lshlrev_b32_e32 v88, 16, v30
	v_lshlrev_b32_e32 v73, 16, v39
	v_and_b32_e32 v91, 0xffff0000, v33
	v_and_b32_e32 v90, 0xffff0000, v30
	v_and_b32_e32 v77, 0xffff0000, v39
	v_lshlrev_b32_e32 v26, 16, v48
	v_lshlrev_b32_e32 v38, 16, v49
	v_and_b32_e32 v39, 0xffff0000, v49
	v_and_b32_e32 v30, 0xffff0000, v48
	v_lshlrev_b32_e32 v48, 16, v151
	v_and_b32_e32 v49, 0xffff0000, v151
	v_lshlrev_b32_e32 v29, 16, v150
	v_and_b32_e32 v33, 0xffff0000, v150
	v_pk_mul_f32 v[150:151], v[6:7], v[70:71] op_sel_hi:[0,1]
	v_exp_f32_e32 v58, v58
	v_mul_f32_e32 v70, 0xbfb8aa3b, v147
	v_exp_f32_e32 v70, v70
	v_lshlrev_b32_e32 v92, 16, v34
	v_add_f32_e32 v58, 1.0, v58
	v_rcp_f32_e32 v158, v58
	v_add_f32_e32 v58, 1.0, v70
	v_rcp_f32_e32 v159, v58
	v_and_b32_e32 v93, 0xffff0000, v34
	v_readlane_b32 s5, v153, s16
	v_lshlrev_b32_e32 v160, 16, v31
	v_pk_mul_f32 v[146:147], v[146:147], v[158:159]
	v_and_b32_e32 v161, 0xffff0000, v31
	v_lshlrev_b32_e32 v80, 16, v42
	v_and_b32_e32 v81, 0xffff0000, v42
	v_lshlrev_b32_e32 v68, 16, v51
	v_and_b32_e32 v69, 0xffff0000, v51
	v_lshlrev_b32_e32 v66, 16, v43
	v_and_b32_e32 v67, 0xffff0000, v43
	v_mov_b32_e32 v162, v91
	v_lshlrev_b32_e32 v57, 16, v50
	v_and_b32_e32 v61, 0xffff0000, v50
	v_lshlrev_b32_e32 v34, 16, v46
	v_and_b32_e32 v35, 0xffff0000, v46
	v_lshlrev_b32_e32 v46, 16, v149
	v_and_b32_e32 v47, 0xffff0000, v149
	v_lshlrev_b32_e32 v50, 16, v152
	v_and_b32_e32 v51, 0xffff0000, v152
	v_lshlrev_b32_e32 v42, 16, v148
	v_and_b32_e32 v43, 0xffff0000, v148
	s_nop 0
	v_pk_mul_f32 v[148:149], v[14:15], v[92:93]
	v_mul_f32_e32 v152, s5, v101
	v_mov_b32_e32 v58, s5
	v_pk_mul_f32 v[158:159], v[146:147], v[146:147]
	v_pk_mul_f32 v[156:157], v[6:7], v[162:163] op_sel:[1,0]
	v_exp_f32_e32 v162, v152
	v_sub_f32_e32 v152, s44, v58
	v_add_f32_e32 v58, v158, v159
	v_pk_fma_f32 v[148:149], v[10:11], v[160:161], v[148:149]
	v_mov_b32_e32 v70, v59
	v_add_f32_dpp v58, v58, v58 row_ror:8 row_mask:0xf bank_mask:0xf bound_ctrl:1
	s_nop 0
	v_pk_fma_f32 v[148:149], v[12:13], v[84:85], v[148:149]
	v_pk_mul_f32 v[160:161], v[22:23], v[86:87]
	v_add_f32_dpp v58, v58, v58 row_ror:4 row_mask:0xf bank_mask:0xf bound_ctrl:1
	s_nop 0
	v_pk_fma_f32 v[148:149], v[16:17], v[80:81], v[148:149]
	v_pk_fma_f32 v[94:95], v[24:25], v[94:95], v[160:161]
	v_add_f32_dpp v58, v58, v58 quad_perm:[2,3,0,1] row_mask:0xf bank_mask:0xf bound_ctrl:1
	v_mul_f32_e32 v158, 0xbfb8aa3b, v148
	v_exp_f32_e32 v158, v158
	v_add_f32_dpp v58, v58, v58 quad_perm:[1,0,3,2] row_mask:0xf bank_mask:0xf bound_ctrl:1
	v_mul_f32_e32 v159, 0xbfb8aa3b, v149
	v_exp_f32_e32 v159, v159
	v_mov_b32_dpp v70, v58 row_bcast:15 row_mask:0xa bank_mask:0xf
	v_add_f32_e32 v58, v58, v70
	v_mov_b32_e32 v70, v59
	v_mul_f32_e32 v152, 0x3fb8aa3b, v152
	v_pk_fma_f32 v[94:95], v[18:19], v[82:83], v[94:95]
	v_mov_b32_dpp v70, v58 row_bcast:31 row_mask:0xc bank_mask:0xf
	v_add_f32_e32 v58, v58, v70
	v_add_f32_e32 v70, 1.0, v158
	v_rcp_f32_e32 v158, v70
	v_add_f32_e32 v70, 1.0, v159
	v_rcp_f32_e32 v159, v70
	v_readlane_b32 s5, v58, 63
	v_pk_fma_f32 v[94:95], v[20:21], v[68:69], v[94:95]
	s_add_i32 s18, s16, s15
	v_pk_mul_f32 v[148:149], v[148:149], v[158:159]
	v_add_f32_e32 v58, s5, v102
	v_pk_mul_f32 v[158:159], v[148:149], v[148:149]
	v_rsq_f32_e32 v58, v58
	v_add_f32_e32 v70, v158, v159
	v_mov_b32_e32 v158, v59
	s_ashr_i32 s19, s18, 31
	v_add_f32_dpp v70, v70, v70 row_ror:8 row_mask:0xf bank_mask:0xf bound_ctrl:1
	v_pk_mul_f32 v[146:147], v[146:147], v[58:59] op_sel_hi:[1,0]
	s_lshl_b64 s[18:19], s[18:19], 11
	v_add_f32_dpp v70, v70, v70 row_ror:4 row_mask:0xf bank_mask:0xf bound_ctrl:1
	v_cvt_pk_bf16_f32 v58, v146, v147
	v_pk_mul_f32 v[146:147], v[146:147], v[162:163] op_sel_hi:[1,0]
	v_add_f32_dpp v70, v70, v70 quad_perm:[2,3,0,1] row_mask:0xf bank_mask:0xf bound_ctrl:1
	v_pk_mul_f32 v[146:147], v[146:147], s[8:9] op_sel_hi:[1,0]
	s_or_b32 s17, s16, 1
	v_add_f32_dpp v70, v70, v70 quad_perm:[1,0,3,2] row_mask:0xf bank_mask:0xf bound_ctrl:1
	v_readlane_b32 s21, v153, s17
	v_mov_b32_e32 v76, v163
	v_mov_b32_dpp v158, v70 row_bcast:15 row_mask:0xa bank_mask:0xf
	v_add_f32_e32 v70, v70, v158
	v_mov_b32_e32 v158, v59
	v_pk_fma_f32 v[90:91], v[2:3], v[90:91], v[156:157] op_sel:[1,0,0]
	v_mov_b32_e32 v78, v77
	v_mov_b32_dpp v158, v70 row_bcast:31 row_mask:0xc bank_mask:0xf
	v_add_f32_e32 v70, v70, v158
	v_exp_f32_e32 v158, v152
	v_readlane_b32 s5, v70, 63
	v_pk_fma_f32 v[90:91], v[4:5], v[76:77], v[90:91] op_sel:[1,0,0]
	v_pk_fma_f32 v[88:89], v[2:3], v[88:89], v[150:151] op_sel_hi:[0,1,1]
	v_add_f32_e32 v70, s5, v102
	v_rsq_f32_e32 v70, v70
	s_mul_i32 s5, s20, 0x880
	v_pk_fma_f32 v[90:91], v[8:9], v[78:79], v[90:91] op_sel:[1,0,0]
	v_pk_fma_f32 v[88:89], v[4:5], v[72:73], v[88:89] op_sel_hi:[0,1,1]
	v_pk_mul_f32 v[148:149], v[148:149], v[70:71] op_sel_hi:[1,0]
	v_add_u32_e32 v70, s5, v145
	v_cvt_pk_bf16_f32 v152, v148, v149
	ds_write2st64_b32 v70, v58, v152 offset1:68
	v_mul_f32_e32 v70, 0xbfb8aa3b, v94
	v_exp_f32_e32 v70, v70
	v_mul_f32_e32 v152, 0xbfb8aa3b, v95
	v_exp_f32_e32 v152, v152
	v_cvt_pk_bf16_f32 v58, v146, v147
	v_lshl_add_u64 v[146:147], v[36:37], 0, s[18:19]
	global_store_dword v[146:147], v58, off
	v_add_f32_e32 v58, 1.0, v70
	v_rcp_f32_e32 v146, v58
	v_add_f32_e32 v58, 1.0, v152
	v_rcp_f32_e32 v147, v58
	v_mov_b32_e32 v70, v59
	v_pk_fma_f32 v[88:89], v[8:9], v[74:75], v[88:89] op_sel_hi:[0,1,1]
	v_mul_f32_e32 v72, 0xbfb8aa3b, v89
	v_pk_mul_f32 v[94:95], v[94:95], v[146:147]
	v_exp_f32_e32 v72, v72
	v_pk_mul_f32 v[146:147], v[94:95], v[94:95]
	v_readlane_b32 s4, v154, s16
	v_add_f32_e32 v58, v146, v147
	v_pk_mul_f32 v[146:147], v[14:15], v[84:85]
	v_readlane_b32 s5, v154, s17
	v_pk_fma_f32 v[92:93], v[10:11], v[92:93], v[146:147]
	v_add_f32_dpp v58, v58, v58 row_ror:8 row_mask:0xf bank_mask:0xf bound_ctrl:1
	v_pk_fma_f32 v[92:93], v[12:13], v[80:81], v[92:93]
	s_or_b32 s22, s16, 2
	v_add_f32_dpp v58, v58, v58 row_ror:4 row_mask:0xf bank_mask:0xf bound_ctrl:1
	v_pk_fma_f32 v[92:93], v[16:17], v[66:67], v[92:93]
	s_add_i32 s48, s22, s15
	v_add_f32_dpp v58, v58, v58 quad_perm:[2,3,0,1] row_mask:0xf bank_mask:0xf bound_ctrl:1
	v_mul_f32_e32 v146, 0xbfb8aa3b, v92
	v_exp_f32_e32 v146, v146
	v_add_f32_dpp v58, v58, v58 quad_perm:[1,0,3,2] row_mask:0xf bank_mask:0xf bound_ctrl:1
	v_mul_f32_e32 v147, 0xbfb8aa3b, v93
	v_exp_f32_e32 v147, v147
	v_mov_b32_dpp v70, v58 row_bcast:15 row_mask:0xa bank_mask:0xf
	v_add_f32_e32 v58, v58, v70
	v_mov_b32_e32 v70, v59
	s_ashr_i32 s49, s48, 31
	s_lshl_b64 s[48:49], s[48:49], 11
	v_mov_b32_dpp v70, v58 row_bcast:31 row_mask:0xc bank_mask:0xf
	v_add_f32_e32 v58, v58, v70
	v_add_f32_e32 v70, 1.0, v146
	v_rcp_f32_e32 v146, v70
	v_add_f32_e32 v70, 1.0, v147
	v_rcp_f32_e32 v147, v70
	v_readlane_b32 s18, v58, 63
	s_or_b32 s23, s16, 3
	v_readlane_b32 s47, v153, s23
	v_pk_mul_f32 v[92:93], v[92:93], v[146:147]
	v_add_f32_e32 v58, s18, v102
	v_pk_mul_f32 v[146:147], v[92:93], v[92:93]
	v_rsq_f32_e32 v58, v58
	v_add_f32_e32 v70, v146, v147
	v_mov_b32_e32 v146, v59
	v_and_b32_e32 v31, 0xffff0000, v144
	v_add_f32_dpp v70, v70, v70 row_ror:8 row_mask:0xf bank_mask:0xf bound_ctrl:1
	v_pk_mul_f32 v[94:95], v[94:95], v[58:59] op_sel_hi:[1,0]
	v_lshlrev_b32_e32 v27, 16, v144
	v_add_f32_dpp v70, v70, v70 row_ror:4 row_mask:0xf bank_mask:0xf bound_ctrl:1
	v_cvt_pk_bf16_f32 v58, v94, v95
	v_and_b32_e32 v144, 15, v106
	v_add_f32_dpp v70, v70, v70 quad_perm:[2,3,0,1] row_mask:0xf bank_mask:0xf bound_ctrl:1
	s_nop 1
	v_add_f32_dpp v70, v70, v70 quad_perm:[1,0,3,2] row_mask:0xf bank_mask:0xf bound_ctrl:1
	s_nop 1
	v_mov_b32_dpp v146, v70 row_bcast:15 row_mask:0xa bank_mask:0xf
	v_add_f32_e32 v70, v70, v146
	v_mov_b32_e32 v146, v59
	s_nop 1
	v_mov_b32_dpp v146, v70 row_bcast:31 row_mask:0xc bank_mask:0xf
	v_add_f32_e32 v70, v70, v146
	v_mul_f32_e32 v146, s21, v101
	v_readlane_b32 s18, v70, 63
	v_exp_f32_e32 v146, v146
	s_nop 0
	v_add_f32_e32 v70, s18, v102
	v_rsq_f32_e32 v70, v70
	s_mul_i32 s18, s17, 0x110
	v_pk_mul_f32 v[94:95], v[94:95], v[146:147] op_sel_hi:[1,0]
	v_mov_b32_e32 v163, v146
	v_pk_mul_f32 v[160:161], v[92:93], v[70:71] op_sel_hi:[1,0]
	v_add_u32_e32 v92, s18, v145
	s_add_i32 s18, s17, s15
	s_ashr_i32 s19, s18, 31
	ds_write_b32 v92, v58
	v_cvt_pk_bf16_f32 v58, v160, v161
	v_pk_mul_f32 v[94:95], v[94:95], s[8:9] op_sel_hi:[1,0]
	s_lshl_b64 s[18:19], s[18:19], 11
	v_mov_b32_e32 v70, s21
	ds_write_b32 v92, v58 offset:17408
	v_cvt_pk_bf16_f32 v58, v94, v95
	v_lshl_add_u64 v[94:95], v[36:37], 0, s[18:19]
	v_sub_f32_e32 v70, s44, v70
	v_mul_f32_e32 v70, 0x3fb8aa3b, v70
	global_store_dword v[94:95], v58, off
	v_mul_f32_e32 v58, 0xbfb8aa3b, v90
	v_exp_f32_e32 v159, v70
	v_exp_f32_e32 v58, v58
	v_mul_f32_e32 v70, 0xbfb8aa3b, v91
	v_exp_f32_e32 v70, v70
	v_mov_b32_e32 v94, v149
	v_add_f32_e32 v58, 1.0, v58
	v_rcp_f32_e32 v156, v58
	v_add_f32_e32 v58, 1.0, v70
	v_mul_f32_e32 v70, 0xbfb8aa3b, v88
	v_exp_f32_e32 v70, v70
	v_rcp_f32_e32 v157, v58
	v_mov_b32_e32 v95, v161
	v_mov_b32_e32 v149, v160
	v_add_f32_e32 v58, 1.0, v70
	v_rcp_f32_e32 v150, v58
	v_add_f32_e32 v58, 1.0, v72
	v_rcp_f32_e32 v151, v58
	v_pk_mul_f32 v[90:91], v[90:91], v[156:157]
	s_lshl_b32 s21, s20, 4
	v_pk_mul_f32 v[164:165], v[94:95], v[158:159]
	v_pk_mul_f32 v[88:89], v[88:89], v[150:151]
	v_pk_mul_f32 v[90:91], v[90:91], s[4:5]
	v_pk_mul_f32 v[88:89], v[88:89], s[4:5]
	v_pk_mul_f32 v[94:95], v[94:95], s[4:5]
	v_pk_mul_f32 v[146:147], v[148:149], s[4:5]
	s_and_b32 s5, s21, 0x3fffffc0
	s_add_i32 s18, s38, s5
	s_lshr_b32 s5, s45, 1
	v_pk_mul_f32 v[146:147], v[146:147], v[162:163]
	s_add_i32 s4, s21, 0
	s_and_b32 s19, s5, 32
	s_lshr_b32 s17, s45, 4
	v_mul_u32_u24_e32 v58, 0x48, v155
	s_add_i32 s5, s18, s19
	s_and_b32 s17, s17, 8
	v_cvt_pk_bf16_f32 v70, v146, v147
	v_lshl_add_u32 v58, v58, 1, s4
	v_pk_mul_f32 v[158:159], v[148:149], v[158:159]
	s_add_i32 s5, s5, s17
	ds_write_b32 v58, v70 offset:53248
	v_cvt_pk_bf16_f32 v70, v88, v89
	v_lshlrev_b32_e32 v88, 7, v155
	v_pk_mul_f32 v[94:95], v[94:95], v[162:163]
	ds_write_b32 v58, v70 offset:34816
	v_cvt_pk_bf16_f32 v70, v158, v159
	v_add_u32_e32 v72, s5, v88
	ds_write_b32 v72, v70
	v_cvt_pk_bf16_f32 v70, v94, v95
	ds_write_b32 v58, v70 offset:53392
	v_cvt_pk_bf16_f32 v70, v90, v91
	v_pk_mul_f32 v[90:91], v[22:23], v[82:83]
	v_or_b32_e32 v89, 0x80, v88
	v_pk_fma_f32 v[86:87], v[24:25], v[86:87], v[90:91]
	ds_write_b32 v58, v70 offset:34960
	v_pk_fma_f32 v[86:87], v[18:19], v[68:69], v[86:87]
	v_cvt_pk_bf16_f32 v70, v164, v165
	v_add_u32_e32 v72, s5, v89
	v_pk_fma_f32 v[86:87], v[20:21], v[64:65], v[86:87]
	ds_write_b32 v72, v70
	v_mul_f32_e32 v70, 0xbfb8aa3b, v86
	v_exp_f32_e32 v70, v70
	v_mul_f32_e32 v72, 0xbfb8aa3b, v87
	v_exp_f32_e32 v72, v72
	v_readlane_b32 s5, v153, s22
	v_add_f32_e32 v70, 1.0, v70
	v_rcp_f32_e32 v90, v70
	v_add_f32_e32 v70, 1.0, v72
	v_rcp_f32_e32 v91, v70
	v_mul_f32_e32 v93, s5, v101
	v_mov_b32_e32 v70, s5
	v_exp_f32_e32 v94, v93
	v_pk_mul_f32 v[86:87], v[86:87], v[90:91]
	v_sub_f32_e32 v93, s44, v70
	v_pk_mul_f32 v[90:91], v[86:87], v[86:87]
	v_mov_b32_e32 v72, v59
	v_add_f32_e32 v70, v90, v91
	v_pk_mul_f32 v[90:91], v[14:15], v[80:81]
	v_pk_mul_f32 v[146:147], v[22:23], v[68:69]
	v_pk_fma_f32 v[84:85], v[10:11], v[84:85], v[90:91]
	v_add_f32_dpp v70, v70, v70 row_ror:8 row_mask:0xf bank_mask:0xf bound_ctrl:1
	v_pk_fma_f32 v[84:85], v[12:13], v[66:67], v[84:85]
	v_pk_fma_f32 v[82:83], v[24:25], v[82:83], v[146:147]
	v_add_f32_dpp v70, v70, v70 row_ror:4 row_mask:0xf bank_mask:0xf bound_ctrl:1
	v_pk_fma_f32 v[84:85], v[16:17], v[62:63], v[84:85]
	v_pk_fma_f32 v[82:83], v[18:19], v[64:65], v[82:83]
	v_add_f32_dpp v70, v70, v70 quad_perm:[2,3,0,1] row_mask:0xf bank_mask:0xf bound_ctrl:1
	v_mul_f32_e32 v90, 0xbfb8aa3b, v84
	v_exp_f32_e32 v90, v90
	v_add_f32_dpp v70, v70, v70 quad_perm:[1,0,3,2] row_mask:0xf bank_mask:0xf bound_ctrl:1
	v_mul_f32_e32 v91, 0xbfb8aa3b, v85
	v_exp_f32_e32 v91, v91
	v_mov_b32_dpp v72, v70 row_bcast:15 row_mask:0xa bank_mask:0xf
	v_add_f32_e32 v70, v70, v72
	v_mov_b32_e32 v72, v59
	v_pk_fma_f32 v[82:83], v[20:21], v[54:55], v[82:83]
	v_pk_mul_f32 v[148:149], v[6:7], v[78:79] op_sel:[1,0]
	v_mov_b32_dpp v72, v70 row_bcast:31 row_mask:0xc bank_mask:0xf
	v_add_f32_e32 v70, v70, v72
	v_add_f32_e32 v72, 1.0, v90
	v_rcp_f32_e32 v90, v72
	v_add_f32_e32 v72, 1.0, v91
	v_rcp_f32_e32 v91, v72
	v_readlane_b32 s5, v70, 63
	v_pk_fma_f32 v[148:149], v[2:3], v[76:77], v[148:149] op_sel:[1,0,0]
	v_pk_mov_b32 v[76:77], v[78:79], v[60:61] op_sel:[1,0]
	v_pk_mul_f32 v[84:85], v[84:85], v[90:91]
	v_add_f32_e32 v70, s5, v102
	v_pk_mul_f32 v[90:91], v[84:85], v[84:85]
	v_rsq_f32_e32 v70, v70
	v_add_f32_e32 v72, v90, v91
	v_mov_b32_e32 v90, v59
	v_pk_fma_f32 v[78:79], v[4:5], v[76:77], v[148:149] op_sel:[1,0,0]
	v_add_f32_dpp v72, v72, v72 row_ror:8 row_mask:0xf bank_mask:0xf bound_ctrl:1
	v_pk_mul_f32 v[86:87], v[86:87], v[70:71] op_sel_hi:[1,0]
	v_pk_fma_f32 v[78:79], v[8:9], v[60:61], v[78:79] op_sel:[1,0,0]
	v_add_f32_dpp v72, v72, v72 row_ror:4 row_mask:0xf bank_mask:0xf bound_ctrl:1
	v_cvt_pk_bf16_f32 v91, v86, v87
	v_pk_mul_f32 v[86:87], v[86:87], v[94:95] op_sel_hi:[1,0]
	v_add_f32_dpp v72, v72, v72 quad_perm:[2,3,0,1] row_mask:0xf bank_mask:0xf bound_ctrl:1
	v_mul_f32_e32 v95, 0xbfb8aa3b, v83
	v_exp_f32_e32 v95, v95
	v_add_f32_dpp v72, v72, v72 quad_perm:[1,0,3,2] row_mask:0xf bank_mask:0xf bound_ctrl:1
	v_pk_mul_f32 v[86:87], v[86:87], s[8:9] op_sel_hi:[1,0]
	v_readlane_b32 s4, v154, s22
	v_mov_b32_dpp v90, v72 row_bcast:15 row_mask:0xa bank_mask:0xf
	v_add_f32_e32 v72, v72, v90
	v_mov_b32_e32 v90, v59
	v_cvt_pk_bf16_f32 v70, v86, v87
	v_lshl_add_u64 v[86:87], v[36:37], 0, s[48:49]
	v_mov_b32_dpp v90, v72 row_bcast:31 row_mask:0xc bank_mask:0xf
	v_add_f32_e32 v72, v72, v90
	global_store_dword v[86:87], v70, off
	v_readlane_b32 s5, v72, 63
	v_mul_f32_e32 v90, 0x3fb8aa3b, v93
	v_exp_f32_e32 v90, v90
	v_add_f32_e32 v72, s5, v102
	v_rsq_f32_e32 v72, v72
	v_readlane_b32 s5, v154, s23
	v_pk_mul_f32 v[84:85], v[84:85], v[72:73] op_sel_hi:[1,0]
	v_mul_f32_e32 v72, 0xbfb8aa3b, v82
	v_exp_f32_e32 v72, v72
	v_cvt_pk_bf16_f32 v93, v84, v85
	v_add_f32_e32 v70, 1.0, v72
	v_rcp_f32_e32 v86, v70
	v_add_f32_e32 v70, 1.0, v95
	v_rcp_f32_e32 v87, v70
	v_mov_b32_e32 v72, v59
	v_pk_mul_f32 v[82:83], v[82:83], v[86:87]
	s_nop 0
	v_pk_mul_f32 v[86:87], v[82:83], v[82:83]
	s_nop 0
	v_add_f32_e32 v70, v86, v87
	v_pk_mul_f32 v[86:87], v[14:15], v[66:67]
	s_nop 0
	v_pk_fma_f32 v[80:81], v[10:11], v[80:81], v[86:87]
	v_add_f32_dpp v70, v70, v70 row_ror:8 row_mask:0xf bank_mask:0xf bound_ctrl:1
	v_pk_fma_f32 v[80:81], v[12:13], v[62:63], v[80:81]
	s_nop 0
	v_add_f32_dpp v70, v70, v70 row_ror:4 row_mask:0xf bank_mask:0xf bound_ctrl:1
	v_pk_fma_f32 v[80:81], v[16:17], v[52:53], v[80:81]
	s_nop 0
	v_add_f32_dpp v70, v70, v70 quad_perm:[2,3,0,1] row_mask:0xf bank_mask:0xf bound_ctrl:1
	v_mul_f32_e32 v86, 0xbfb8aa3b, v80
	v_exp_f32_e32 v86, v86
	v_add_f32_dpp v70, v70, v70 quad_perm:[1,0,3,2] row_mask:0xf bank_mask:0xf bound_ctrl:1
	v_mul_f32_e32 v87, 0xbfb8aa3b, v81
	v_exp_f32_e32 v87, v87
	v_mov_b32_dpp v72, v70 row_bcast:15 row_mask:0xa bank_mask:0xf
	v_add_f32_e32 v70, v70, v72
	v_mov_b32_e32 v72, v59
	s_nop 1
	v_mov_b32_dpp v72, v70 row_bcast:31 row_mask:0xc bank_mask:0xf
	v_add_f32_e32 v70, v70, v72
	v_add_f32_e32 v72, 1.0, v86
	v_rcp_f32_e32 v86, v72
	v_add_f32_e32 v72, 1.0, v87
	v_rcp_f32_e32 v87, v72
	v_readlane_b32 s48, v70, 63
	v_pk_mul_f32 v[80:81], v[80:81], v[86:87]
	s_nop 0
	v_pk_mul_f32 v[86:87], v[80:81], v[80:81]
	v_add_f32_e32 v70, s48, v102
	v_add_f32_e32 v72, v86, v87
	v_mov_b32_e32 v86, v59
	v_rsq_f32_e32 v70, v70
	v_add_f32_dpp v72, v72, v72 row_ror:8 row_mask:0xf bank_mask:0xf bound_ctrl:1
	v_pk_mul_f32 v[82:83], v[82:83], v[70:71] op_sel_hi:[1,0]
	s_nop 0
	v_add_f32_dpp v72, v72, v72 row_ror:4 row_mask:0xf bank_mask:0xf bound_ctrl:1
	v_cvt_pk_bf16_f32 v70, v82, v83
	ds_write2_b32 v92, v91, v70 offset0:68 offset1:136
	v_add_f32_dpp v72, v72, v72 quad_perm:[2,3,0,1] row_mask:0xf bank_mask:0xf bound_ctrl:1
	s_nop 1
	v_add_f32_dpp v72, v72, v72 quad_perm:[1,0,3,2] row_mask:0xf bank_mask:0xf bound_ctrl:1
	s_nop 1
	v_mov_b32_dpp v86, v72 row_bcast:15 row_mask:0xa bank_mask:0xf
	v_add_f32_e32 v72, v72, v86
	v_mov_b32_e32 v86, v59
	s_nop 1
	v_mov_b32_dpp v86, v72 row_bcast:31 row_mask:0xc bank_mask:0xf
	v_add_f32_e32 v72, v72, v86
	v_mul_f32_e32 v86, s47, v101
	v_readlane_b32 s48, v72, 63
	v_exp_f32_e32 v86, v86
	s_nop 0
	v_add_f32_e32 v72, s48, v102
	v_rsq_f32_e32 v72, v72
	s_add_i32 s48, s23, s15
	v_pk_mul_f32 v[82:83], v[82:83], v[86:87] op_sel_hi:[1,0]
	s_ashr_i32 s49, s48, 31
	v_pk_mul_f32 v[80:81], v[80:81], v[72:73] op_sel_hi:[1,0]
	v_add_u32_e32 v72, 0x4400, v92
	v_cvt_pk_bf16_f32 v70, v80, v81
	ds_write2_b32 v72, v93, v70 offset0:68 offset1:136
	v_pk_mul_f32 v[82:83], v[82:83], s[8:9] op_sel_hi:[1,0]
	s_lshl_b64 s[48:49], s[48:49], 11
	v_mov_b32_e32 v72, s47
	v_cvt_pk_bf16_f32 v70, v82, v83
	v_lshl_add_u64 v[82:83], v[36:37], 0, s[48:49]
	v_sub_f32_e32 v72, s44, v72
	v_mul_f32_e32 v72, 0x3fb8aa3b, v72
	global_store_dword v[82:83], v70, off
	v_mul_f32_e32 v70, 0xbfb8aa3b, v78
	v_exp_f32_e32 v91, v72
	v_exp_f32_e32 v70, v70
	v_mul_f32_e32 v72, 0xbfb8aa3b, v79
	v_exp_f32_e32 v72, v72
	v_mov_b32_e32 v82, v85
	v_add_f32_e32 v70, 1.0, v70
	v_mov_b32_e32 v83, v81
	v_mov_b32_e32 v85, v80
	v_rcp_f32_e32 v80, v70
	v_add_f32_e32 v81, 1.0, v72
	v_mov_b32_e32 v72, v71
	v_mov_b32_e32 v70, v73
	v_mov_b32_e32 v71, v75
	v_pk_mul_f32 v[70:71], v[6:7], v[70:71] op_sel_hi:[0,1]
	v_pk_fma_f32 v[72:73], v[2:3], v[72:73], v[70:71] op_sel_hi:[0,1,1]
	v_pk_mov_b32 v[70:71], v[74:75], v[56:57] op_sel:[1,0]
	v_rcp_f32_e32 v81, v81
	v_pk_fma_f32 v[72:73], v[4:5], v[70:71], v[72:73] op_sel_hi:[0,1,1]
	v_pk_fma_f32 v[72:73], v[8:9], v[56:57], v[72:73] op_sel_hi:[0,1,1]
	v_mul_f32_e32 v74, 0xbfb8aa3b, v72
	v_mul_f32_e32 v75, 0xbfb8aa3b, v73
	v_exp_f32_e32 v74, v74
	v_exp_f32_e32 v75, v75
	v_pk_mul_f32 v[78:79], v[78:79], v[80:81]
	v_pk_mul_f32 v[80:81], v[84:85], s[4:5]
	v_add_f32_e32 v74, 1.0, v74
	v_add_f32_e32 v75, 1.0, v75
	v_rcp_f32_e32 v74, v74
	v_rcp_f32_e32 v75, v75
	v_pk_mul_f32 v[78:79], v[78:79], s[4:5]
	v_mov_b32_e32 v95, v86
	v_pk_mul_f32 v[146:147], v[82:83], v[90:91]
	v_pk_mul_f32 v[72:73], v[72:73], v[74:75]
	v_pk_mul_f32 v[74:75], v[82:83], s[4:5]
	v_pk_mul_f32 v[72:73], v[72:73], s[4:5]
	s_and_b32 s4, s22, 0x1fffffe2
	s_lshl_b32 s4, s4, 1
	s_add_i32 s4, s38, s4
	s_add_i32 s4, s4, s19
	v_pk_mul_f32 v[90:91], v[84:85], v[90:91]
	v_pk_mul_f32 v[80:81], v[80:81], v[94:95]
	s_add_i32 s4, s4, s17
	v_cvt_pk_bf16_f32 v72, v72, v73
	v_pk_mul_f32 v[74:75], v[74:75], v[94:95]
	v_cvt_pk_bf16_f32 v80, v80, v81
	ds_write_b32 v58, v72 offset:34820
	v_cvt_pk_bf16_f32 v72, v90, v91
	v_add_u32_e32 v73, s4, v88
	ds_write_b32 v58, v80 offset:53252
	ds_write_b32 v73, v72
	v_cvt_pk_bf16_f32 v72, v74, v75
	ds_write_b32 v58, v72 offset:53396
	v_cvt_pk_bf16_f32 v72, v78, v79
	ds_write_b32 v58, v72 offset:34964
	v_cvt_pk_bf16_f32 v72, v146, v147
	v_add_u32_e32 v73, s4, v89
	ds_write_b32 v73, v72
	v_pk_mul_f32 v[72:73], v[22:23], v[64:65]
	v_mov_b32_e32 v79, v59
	v_pk_fma_f32 v[68:69], v[24:25], v[68:69], v[72:73]
	s_or_b32 s19, s16, 4
	v_pk_fma_f32 v[68:69], v[18:19], v[54:55], v[68:69]
	v_readlane_b32 s5, v153, s19
	v_pk_fma_f32 v[68:69], v[20:21], v[44:45], v[68:69]
	s_add_i32 s22, s19, s15
	v_mul_f32_e32 v72, 0xbfb8aa3b, v68
	v_mul_f32_e32 v73, 0xbfb8aa3b, v69
	v_exp_f32_e32 v72, v72
	v_exp_f32_e32 v73, v73
	v_mul_f32_e32 v74, s5, v101
	v_mov_b32_e32 v75, s5
	v_add_f32_e32 v72, 1.0, v72
	v_add_f32_e32 v73, 1.0, v73
	v_rcp_f32_e32 v72, v72
	v_rcp_f32_e32 v73, v73
	v_sub_f32_e32 v75, s44, v75
	v_exp_f32_e32 v74, v74
	s_ashr_i32 s23, s22, 31
	v_pk_mul_f32 v[68:69], v[68:69], v[72:73]
	s_lshl_b64 s[22:23], s[22:23], 11
	v_pk_mul_f32 v[72:73], v[68:69], v[68:69]
	v_readlane_b32 s4, v154, s19
	v_add_f32_e32 v72, v72, v73
	v_mov_b32_e32 v73, v59
	s_nop 0
	v_add_f32_dpp v72, v72, v72 row_ror:8 row_mask:0xf bank_mask:0xf bound_ctrl:1
	s_nop 1
	v_add_f32_dpp v72, v72, v72 row_ror:4 row_mask:0xf bank_mask:0xf bound_ctrl:1
	s_nop 1
	v_add_f32_dpp v72, v72, v72 quad_perm:[2,3,0,1] row_mask:0xf bank_mask:0xf bound_ctrl:1
	s_nop 1
	v_add_f32_dpp v72, v72, v72 quad_perm:[1,0,3,2] row_mask:0xf bank_mask:0xf bound_ctrl:1
	s_nop 1
	v_mov_b32_dpp v73, v72 row_bcast:15 row_mask:0xa bank_mask:0xf
	v_add_f32_e32 v78, v72, v73
	v_pk_mul_f32 v[72:73], v[14:15], v[62:63]
	s_nop 0
	v_pk_fma_f32 v[66:67], v[10:11], v[66:67], v[72:73]
	v_mov_b32_dpp v79, v78 row_bcast:31 row_mask:0xc bank_mask:0xf
	v_pk_fma_f32 v[66:67], v[12:13], v[52:53], v[66:67]
	v_add_f32_e32 v78, v78, v79
	v_pk_fma_f32 v[66:67], v[16:17], v[34:35], v[66:67]
	v_readlane_b32 s5, v78, 63
	v_mul_f32_e32 v72, 0xbfb8aa3b, v66
	v_mul_f32_e32 v73, 0xbfb8aa3b, v67
	v_exp_f32_e32 v72, v72
	v_exp_f32_e32 v73, v73
	v_add_f32_e32 v78, s5, v102
	v_rsq_f32_e32 v78, v78
	v_add_f32_e32 v72, 1.0, v72
	v_add_f32_e32 v73, 1.0, v73
	v_rcp_f32_e32 v72, v72
	v_rcp_f32_e32 v73, v73
	v_pk_mul_f32 v[68:69], v[68:69], v[78:79] op_sel_hi:[1,0]
	v_pk_mul_f32 v[66:67], v[66:67], v[72:73]
	s_nop 0
	v_pk_mul_f32 v[72:73], v[66:67], v[66:67]
	s_nop 0
	v_add_f32_e32 v72, v72, v73
	v_mov_b32_e32 v73, v59
	s_nop 0
	v_add_f32_dpp v72, v72, v72 row_ror:8 row_mask:0xf bank_mask:0xf bound_ctrl:1
	s_nop 1
	v_add_f32_dpp v72, v72, v72 row_ror:4 row_mask:0xf bank_mask:0xf bound_ctrl:1
	s_nop 1
	v_add_f32_dpp v72, v72, v72 quad_perm:[2,3,0,1] row_mask:0xf bank_mask:0xf bound_ctrl:1
	s_nop 1
	v_add_f32_dpp v72, v72, v72 quad_perm:[1,0,3,2] row_mask:0xf bank_mask:0xf bound_ctrl:1
	s_nop 1
	v_mov_b32_dpp v73, v72 row_bcast:15 row_mask:0xa bank_mask:0xf
	v_add_f32_e32 v72, v72, v73
	v_mov_b32_e32 v73, v59
	s_nop 1
	v_mov_b32_dpp v73, v72 row_bcast:31 row_mask:0xc bank_mask:0xf
	v_add_f32_e32 v72, v72, v73
	v_mul_f32_e32 v73, 0x3fb8aa3b, v75
	v_readlane_b32 s5, v72, 63
	v_exp_f32_e32 v80, v73
	v_cvt_pk_bf16_f32 v75, v68, v69
	v_add_f32_e32 v72, s5, v102
	v_rsq_f32_e32 v72, v72
	v_pk_mul_f32 v[68:69], v[68:69], v[74:75] op_sel_hi:[1,0]
	v_pk_mul_f32 v[66:67], v[66:67], v[72:73] op_sel_hi:[1,0]
	v_pk_mul_f32 v[72:73], v[22:23], v[54:55]
	v_pk_mul_f32 v[68:69], v[68:69], s[8:9] op_sel_hi:[1,0]
	v_pk_fma_f32 v[64:65], v[24:25], v[64:65], v[72:73]
	v_cvt_pk_bf16_f32 v78, v68, v69
	v_pk_fma_f32 v[64:65], v[18:19], v[44:45], v[64:65]
	v_lshl_add_u64 v[68:69], v[36:37], 0, s[22:23]
	v_pk_fma_f32 v[64:65], v[20:21], v[46:47], v[64:65]
	global_store_dword v[68:69], v78, off
	v_mul_f32_e32 v72, 0xbfb8aa3b, v64
	v_mul_f32_e32 v73, 0xbfb8aa3b, v65
	v_exp_f32_e32 v72, v72
	v_exp_f32_e32 v73, v73
	s_or_b32 s22, s16, 5
	v_readlane_b32 s47, v153, s22
	v_add_f32_e32 v68, 1.0, v72
	v_add_f32_e32 v69, 1.0, v73
	v_rcp_f32_e32 v68, v68
	v_rcp_f32_e32 v69, v69
	v_mov_b32_e32 v73, v59
	v_cvt_pk_bf16_f32 v79, v66, v67
	v_readlane_b32 s5, v154, s22
	v_pk_mul_f32 v[64:65], v[64:65], v[68:69]
	s_add_i32 s22, s22, s15
	v_pk_mul_f32 v[68:69], v[64:65], v[64:65]
	s_nop 0
	v_add_f32_e32 v68, v68, v69
	v_mov_b32_e32 v69, v59
	s_nop 0
	v_add_f32_dpp v68, v68, v68 row_ror:8 row_mask:0xf bank_mask:0xf bound_ctrl:1
	s_nop 1
	v_add_f32_dpp v68, v68, v68 row_ror:4 row_mask:0xf bank_mask:0xf bound_ctrl:1
	s_nop 1
	v_add_f32_dpp v68, v68, v68 quad_perm:[2,3,0,1] row_mask:0xf bank_mask:0xf bound_ctrl:1
	s_nop 1
	v_add_f32_dpp v68, v68, v68 quad_perm:[1,0,3,2] row_mask:0xf bank_mask:0xf bound_ctrl:1
	s_nop 1
	v_mov_b32_dpp v69, v68 row_bcast:15 row_mask:0xa bank_mask:0xf
	v_add_f32_e32 v72, v68, v69
	v_pk_mul_f32 v[68:69], v[14:15], v[52:53]
	s_nop 0
	v_pk_fma_f32 v[62:63], v[10:11], v[62:63], v[68:69]
	v_mov_b32_dpp v73, v72 row_bcast:31 row_mask:0xc bank_mask:0xf
	v_pk_fma_f32 v[62:63], v[12:13], v[34:35], v[62:63]
	v_add_f32_e32 v72, v72, v73
	v_pk_fma_f32 v[62:63], v[16:17], v[38:39], v[62:63]
	v_readlane_b32 s23, v72, 63
	v_mul_f32_e32 v68, 0xbfb8aa3b, v62
	v_mul_f32_e32 v69, 0xbfb8aa3b, v63
	v_exp_f32_e32 v68, v68
	v_exp_f32_e32 v69, v69
	v_add_f32_e32 v72, s23, v102
	v_rsq_f32_e32 v72, v72
	v_add_f32_e32 v68, 1.0, v68
	v_add_f32_e32 v69, 1.0, v69
	v_rcp_f32_e32 v68, v68
	v_rcp_f32_e32 v69, v69
	v_pk_mul_f32 v[64:65], v[64:65], v[72:73] op_sel_hi:[1,0]
	v_pk_mul_f32 v[72:73], v[6:7], v[60:61] op_sel:[1,0]
	v_pk_mov_b32 v[60:61], v[60:61], v[30:31] op_sel:[1,0]
	v_pk_mul_f32 v[62:63], v[62:63], v[68:69]
	v_pk_fma_f32 v[72:73], v[2:3], v[76:77], v[72:73] op_sel:[1,0,0]
	v_pk_mul_f32 v[68:69], v[62:63], v[62:63]
	v_pk_fma_f32 v[72:73], v[4:5], v[60:61], v[72:73] op_sel:[1,0,0]
	v_add_f32_e32 v68, v68, v69
	v_mov_b32_e32 v69, v59
	v_pk_fma_f32 v[72:73], v[8:9], v[30:31], v[72:73] op_sel:[1,0,0]
	v_add_f32_dpp v68, v68, v68 row_ror:8 row_mask:0xf bank_mask:0xf bound_ctrl:1
	v_pk_mul_f32 v[76:77], v[6:7], v[56:57] op_sel_hi:[0,1]
	v_pk_fma_f32 v[70:71], v[2:3], v[70:71], v[76:77] op_sel_hi:[0,1,1]
	v_add_f32_dpp v68, v68, v68 row_ror:4 row_mask:0xf bank_mask:0xf bound_ctrl:1
	v_pk_mov_b32 v[56:57], v[56:57], v[26:27] op_sel:[1,0]
	s_nop 0
	v_add_f32_dpp v68, v68, v68 quad_perm:[2,3,0,1] row_mask:0xf bank_mask:0xf bound_ctrl:1
	v_pk_fma_f32 v[70:71], v[4:5], v[56:57], v[70:71] op_sel_hi:[0,1,1]
	v_pk_fma_f32 v[70:71], v[8:9], v[26:27], v[70:71] op_sel_hi:[0,1,1]
	v_add_f32_dpp v68, v68, v68 quad_perm:[1,0,3,2] row_mask:0xf bank_mask:0xf bound_ctrl:1
	v_mul_f32_e32 v76, 0xbfb8aa3b, v71
	v_exp_f32_e32 v77, v76
	v_mov_b32_dpp v69, v68 row_bcast:15 row_mask:0xa bank_mask:0xf
	v_add_f32_e32 v68, v68, v69
	v_mov_b32_e32 v69, v59
	s_nop 1
	v_mov_b32_dpp v69, v68 row_bcast:31 row_mask:0xc bank_mask:0xf
	v_add_f32_e32 v68, v68, v69
	v_mul_f32_e32 v69, s47, v101
	v_readlane_b32 s23, v68, 63
	v_exp_f32_e32 v78, v69
	s_nop 0
	v_add_f32_e32 v68, s23, v102
	v_rsq_f32_e32 v68, v68
	s_ashr_i32 s23, s22, 31
	s_lshl_b64 s[22:23], s[22:23], 11
	v_pk_mul_f32 v[62:63], v[62:63], v[68:69] op_sel_hi:[1,0]
	v_cvt_pk_bf16_f32 v68, v64, v65
	v_add_u32_e32 v69, 0x200, v92
	v_pk_mul_f32 v[64:65], v[64:65], v[78:79] op_sel_hi:[1,0]
	ds_write2_b32 v69, v75, v68 offset0:76 offset1:144
	v_cvt_pk_bf16_f32 v68, v62, v63
	v_add_u32_e32 v69, 0x4600, v92
	v_pk_mul_f32 v[64:65], v[64:65], s[8:9] op_sel_hi:[1,0]
	ds_write2_b32 v69, v79, v68 offset0:76 offset1:144
	v_cvt_pk_bf16_f32 v68, v64, v65
	v_lshl_add_u64 v[64:65], v[36:37], 0, s[22:23]
	global_store_dword v[64:65], v68, off
	v_mov_b32_e32 v64, v67
	v_mov_b32_e32 v65, v63
	v_mul_f32_e32 v63, 0xbfb8aa3b, v72
	v_mul_f32_e32 v67, 0xbfb8aa3b, v73
	v_exp_f32_e32 v63, v63
	v_exp_f32_e32 v75, v67
	v_mov_b32_e32 v67, v62
	v_mov_b32_e32 v69, s47
	v_add_f32_e32 v62, 1.0, v63
	v_add_f32_e32 v63, 1.0, v75
	v_mul_f32_e32 v75, 0xbfb8aa3b, v70
	v_exp_f32_e32 v75, v75
	v_sub_f32_e32 v69, s44, v69
	v_mul_f32_e32 v69, 0x3fb8aa3b, v69
	v_rcp_f32_e32 v62, v62
	v_add_f32_e32 v75, 1.0, v75
	v_rcp_f32_e32 v76, v75
	v_add_f32_e32 v75, 1.0, v77
	v_rcp_f32_e32 v63, v63
	v_rcp_f32_e32 v77, v75
	v_exp_f32_e32 v81, v69
	v_mov_b32_e32 v75, v78
	v_pk_mul_f32 v[62:63], v[72:73], v[62:63]
	v_pk_mul_f32 v[70:71], v[70:71], v[76:77]
	v_pk_mul_f32 v[68:69], v[64:65], v[80:81]
	v_pk_mul_f32 v[80:81], v[66:67], v[80:81]
	v_pk_mul_f32 v[62:63], v[62:63], s[4:5]
	v_pk_mul_f32 v[70:71], v[70:71], s[4:5]
	v_pk_mul_f32 v[64:65], v[64:65], s[4:5]
	v_pk_mul_f32 v[66:67], v[66:67], s[4:5]
	s_lshl_b32 s4, s19, 2
	v_pk_mul_f32 v[66:67], v[66:67], v[74:75]
	s_and_b32 s4, s4, 48
	s_add_i32 s4, s18, s4
	v_cvt_pk_bf16_f32 v66, v66, v67
	s_add_i32 s4, s4, s17
	ds_write_b32 v58, v66 offset:53256
	v_cvt_pk_bf16_f32 v66, v70, v71
	v_pk_mul_f32 v[64:65], v[64:65], v[74:75]
	ds_write_b32 v58, v66 offset:34824
	v_cvt_pk_bf16_f32 v66, v80, v81
	v_add_u32_e32 v67, s4, v88
	v_cvt_pk_bf16_f32 v62, v62, v63
	ds_write_b32 v67, v66
	v_cvt_pk_bf16_f32 v64, v64, v65
	ds_write_b32 v58, v62 offset:34968
	v_cvt_pk_bf16_f32 v62, v68, v69
	v_add_u32_e32 v63, s4, v89
	ds_write_b32 v58, v64 offset:53400
	ds_write_b32 v63, v62
	v_pk_mul_f32 v[62:63], v[22:23], v[44:45]
	v_pk_mul_f32 v[22:23], v[22:23], v[46:47]
	v_pk_fma_f32 v[54:55], v[24:25], v[54:55], v[62:63]
	v_pk_fma_f32 v[22:23], v[24:25], v[44:45], v[22:23]
	v_pk_fma_f32 v[54:55], v[18:19], v[46:47], v[54:55]
	v_pk_fma_f32 v[18:19], v[18:19], v[48:49], v[22:23]
	v_pk_fma_f32 v[54:55], v[20:21], v[48:49], v[54:55]
	v_pk_fma_f32 v[18:19], v[20:21], v[50:51], v[18:19]
	v_mul_f32_e32 v62, 0xbfb8aa3b, v54
	v_mul_f32_e32 v63, 0xbfb8aa3b, v55
	v_exp_f32_e32 v62, v62
	v_exp_f32_e32 v63, v63
	v_mul_f32_e32 v20, 0xbfb8aa3b, v18
	v_mul_f32_e32 v21, 0xbfb8aa3b, v19
	v_add_f32_e32 v62, 1.0, v62
	v_add_f32_e32 v63, 1.0, v63
	v_rcp_f32_e32 v62, v62
	v_rcp_f32_e32 v63, v63
	v_exp_f32_e32 v20, v20
	v_exp_f32_e32 v21, v21
	v_mov_b32_e32 v67, v59
	v_pk_mul_f32 v[54:55], v[54:55], v[62:63]
	v_add_f32_e32 v20, 1.0, v20
	v_pk_mul_f32 v[62:63], v[54:55], v[54:55]
	v_add_f32_e32 v21, 1.0, v21
	v_add_f32_e32 v62, v62, v63
	v_mov_b32_e32 v63, v59
	v_rcp_f32_e32 v20, v20
	v_add_f32_dpp v62, v62, v62 row_ror:8 row_mask:0xf bank_mask:0xf bound_ctrl:1
	v_rcp_f32_e32 v21, v21
	s_or_b32 s18, s16, 6
	v_add_f32_dpp v62, v62, v62 row_ror:4 row_mask:0xf bank_mask:0xf bound_ctrl:1
	v_readlane_b32 s5, v153, s18
	v_pk_mul_f32 v[18:19], v[18:19], v[20:21]
	v_add_f32_dpp v62, v62, v62 quad_perm:[2,3,0,1] row_mask:0xf bank_mask:0xf bound_ctrl:1
	v_pk_mul_f32 v[20:21], v[18:19], v[18:19]
	v_mul_f32_e32 v64, s5, v101
	v_add_f32_dpp v62, v62, v62 quad_perm:[1,0,3,2] row_mask:0xf bank_mask:0xf bound_ctrl:1
	v_mov_b32_e32 v65, s5
	v_add_f32_e32 v20, v20, v21
	v_mov_b32_dpp v63, v62 row_bcast:15 row_mask:0xa bank_mask:0xf
	v_add_f32_e32 v66, v62, v63
	v_pk_mul_f32 v[62:63], v[14:15], v[34:35]
	v_pk_mul_f32 v[14:15], v[14:15], v[38:39]
	v_pk_fma_f32 v[52:53], v[10:11], v[52:53], v[62:63]
	v_pk_fma_f32 v[10:11], v[10:11], v[34:35], v[14:15]
	v_pk_fma_f32 v[52:53], v[12:13], v[38:39], v[52:53]
	v_pk_fma_f32 v[10:11], v[12:13], v[40:41], v[10:11]
	v_pk_fma_f32 v[52:53], v[16:17], v[40:41], v[52:53]
	v_pk_fma_f32 v[10:11], v[16:17], v[42:43], v[10:11]
	v_mul_f32_e32 v62, 0xbfb8aa3b, v52
	v_mul_f32_e32 v63, 0xbfb8aa3b, v53
	v_exp_f32_e32 v62, v62
	v_exp_f32_e32 v63, v63
	v_mul_f32_e32 v12, 0xbfb8aa3b, v10
	v_mul_f32_e32 v13, 0xbfb8aa3b, v11
	v_add_f32_e32 v62, 1.0, v62
	v_add_f32_e32 v63, 1.0, v63
	v_rcp_f32_e32 v62, v62
	v_rcp_f32_e32 v63, v63
	v_exp_f32_e32 v12, v12
	v_exp_f32_e32 v13, v13
	v_mov_b32_dpp v67, v66 row_bcast:31 row_mask:0xc bank_mask:0xf
	v_pk_mul_f32 v[52:53], v[52:53], v[62:63]
	v_add_f32_e32 v12, 1.0, v12
	v_pk_mul_f32 v[62:63], v[52:53], v[52:53]
	v_add_f32_e32 v13, 1.0, v13
	v_add_f32_e32 v62, v62, v63
	v_rcp_f32_e32 v12, v12
	v_rcp_f32_e32 v13, v13
	v_add_f32_dpp v62, v62, v62 row_ror:8 row_mask:0xf bank_mask:0xf bound_ctrl:1
	v_mov_b32_e32 v63, v59
	v_add_f32_e32 v66, v66, v67
	v_add_f32_dpp v62, v62, v62 row_ror:4 row_mask:0xf bank_mask:0xf bound_ctrl:1
	v_pk_mul_f32 v[10:11], v[10:11], v[12:13]
	v_readlane_b32 s5, v66, 63
	v_add_f32_dpp v62, v62, v62 quad_perm:[2,3,0,1] row_mask:0xf bank_mask:0xf bound_ctrl:1
	v_pk_mul_f32 v[12:13], v[10:11], v[10:11]
	v_add_f32_e32 v66, s5, v102
	v_add_f32_dpp v62, v62, v62 quad_perm:[1,0,3,2] row_mask:0xf bank_mask:0xf bound_ctrl:1
	v_add_f32_dpp v20, v20, v20 row_ror:8 row_mask:0xf bank_mask:0xf bound_ctrl:1
	v_add_f32_e32 v12, v12, v13
	v_mov_b32_dpp v63, v62 row_bcast:15 row_mask:0xa bank_mask:0xf
	v_add_f32_e32 v62, v62, v63
	v_mov_b32_e32 v63, v59
	v_rsq_f32_e32 v66, v66
	v_add_f32_dpp v20, v20, v20 row_ror:4 row_mask:0xf bank_mask:0xf bound_ctrl:1
	v_mov_b32_dpp v63, v62 row_bcast:31 row_mask:0xc bank_mask:0xf
	v_add_f32_e32 v62, v62, v63
	v_add_f32_dpp v12, v12, v12 row_ror:8 row_mask:0xf bank_mask:0xf bound_ctrl:1
	v_readlane_b32 s5, v62, 63
	v_exp_f32_e32 v64, v64
	v_add_f32_dpp v20, v20, v20 quad_perm:[2,3,0,1] row_mask:0xf bank_mask:0xf bound_ctrl:1
	v_add_f32_e32 v62, s5, v102
	v_rsq_f32_e32 v62, v62
	v_add_f32_dpp v12, v12, v12 row_ror:4 row_mask:0xf bank_mask:0xf bound_ctrl:1
	v_add_f32_dpp v20, v20, v20 quad_perm:[1,0,3,2] row_mask:0xf bank_mask:0xf bound_ctrl:1
	v_mov_b32_e32 v21, v59
	v_add_f32_dpp v12, v12, v12 quad_perm:[2,3,0,1] row_mask:0xf bank_mask:0xf bound_ctrl:1
	v_sub_f32_e32 v65, s44, v65
	v_mov_b32_dpp v21, v20 row_bcast:15 row_mask:0xa bank_mask:0xf
	v_add_f32_dpp v12, v12, v12 quad_perm:[1,0,3,2] row_mask:0xf bank_mask:0xf bound_ctrl:1
	v_mov_b32_e32 v13, v59
	v_mul_f32_e32 v63, 0x3fb8aa3b, v65
	v_pk_mul_f32 v[54:55], v[54:55], v[66:67] op_sel_hi:[1,0]
	s_add_i32 s22, s18, s15
	v_add_f32_e32 v20, v20, v21
	v_mov_b32_e32 v21, v59
	v_mov_b32_dpp v13, v12 row_bcast:15 row_mask:0xa bank_mask:0xf
	v_pk_mul_f32 v[52:53], v[52:53], v[62:63] op_sel_hi:[1,0]
	v_cvt_pk_bf16_f32 v62, v54, v55
	v_pk_mul_f32 v[54:55], v[54:55], v[64:65] op_sel_hi:[1,0]
	s_ashr_i32 s23, s22, 31
	v_mov_b32_dpp v21, v20 row_bcast:31 row_mask:0xc bank_mask:0xf
	v_add_f32_e32 v12, v12, v13
	v_mov_b32_e32 v13, v59
	v_pk_mul_f32 v[54:55], v[54:55], s[8:9] op_sel_hi:[1,0]
	s_lshl_b64 s[22:23], s[22:23], 11
	v_add_f32_e32 v14, v20, v21
	v_mov_b32_dpp v13, v12 row_bcast:31 row_mask:0xc bank_mask:0xf
	v_cvt_pk_bf16_f32 v65, v54, v55
	v_lshl_add_u64 v[54:55], v[36:37], 0, s[22:23]
	v_readlane_b32 s22, v14, 63
	v_add_f32_e32 v12, v12, v13
	s_or_b32 s16, s16, 7
	v_add_f32_e32 v14, s22, v102
	v_readlane_b32 s22, v12, 63
	v_rsq_f32_e32 v14, v14
	v_readlane_b32 s19, v153, s16
	v_add_f32_e32 v12, s22, v102
	v_rsq_f32_e32 v12, v12
	v_mul_f32_e32 v13, s19, v101
	v_exp_f32_e32 v16, v13
	v_pk_mul_f32 v[14:15], v[18:19], v[14:15] op_sel_hi:[1,0]
	v_pk_mul_f32 v[10:11], v[10:11], v[12:13] op_sel_hi:[1,0]
	v_cvt_pk_bf16_f32 v12, v14, v15
	v_add_u32_e32 v13, 0x400, v92
	v_exp_f32_e32 v68, v63
	v_cvt_pk_bf16_f32 v63, v52, v53
	ds_write2_b32 v13, v62, v12 offset0:84 offset1:152
	v_cvt_pk_bf16_f32 v12, v10, v11
	v_add_u32_e32 v13, 0x4800, v92
	s_add_i32 s22, s16, s15
	v_pk_mul_f32 v[18:19], v[6:7], v[30:31] op_sel:[1,0]
	v_pk_mul_f32 v[6:7], v[6:7], v[26:27] op_sel_hi:[0,1]
	ds_write2_b32 v13, v63, v12 offset0:84 offset1:152
	v_pk_mul_f32 v[12:13], v[14:15], v[16:17] op_sel_hi:[1,0]
	s_ashr_i32 s23, s22, 31
	v_pk_fma_f32 v[18:19], v[2:3], v[60:61], v[18:19] op_sel:[1,0,0]
	v_pk_mov_b32 v[20:21], v[30:31], v[32:33] op_sel:[1,0]
	v_pk_fma_f32 v[2:3], v[2:3], v[56:57], v[6:7] op_sel_hi:[0,1,1]
	v_pk_mov_b32 v[6:7], v[26:27], v[28:29] op_sel:[1,0]
	v_pk_mul_f32 v[12:13], v[12:13], s[8:9] op_sel_hi:[1,0]
	s_lshl_b64 s[22:23], s[22:23], 11
	v_pk_fma_f32 v[18:19], v[4:5], v[20:21], v[18:19] op_sel:[1,0,0]
	v_pk_fma_f32 v[2:3], v[4:5], v[6:7], v[2:3] op_sel_hi:[0,1,1]
	v_cvt_pk_bf16_f32 v14, v12, v13
	v_lshl_add_u64 v[12:13], v[36:37], 0, s[22:23]
	v_pk_fma_f32 v[18:19], v[8:9], v[32:33], v[18:19] op_sel:[1,0,0]
	v_pk_fma_f32 v[2:3], v[8:9], v[28:29], v[2:3] op_sel_hi:[0,1,1]
	global_store_dword v[12:13], v14, off
	v_mov_b32_e32 v13, v11
	v_mul_f32_e32 v11, 0xbfb8aa3b, v18
	v_mul_f32_e32 v17, 0xbfb8aa3b, v19
	v_mul_f32_e32 v4, 0xbfb8aa3b, v2
	v_mul_f32_e32 v5, 0xbfb8aa3b, v3
	v_exp_f32_e32 v11, v11
	v_exp_f32_e32 v17, v17
	v_exp_f32_e32 v4, v4
	v_exp_f32_e32 v5, v5
	v_mov_b32_e32 v12, v53
	v_mov_b32_e32 v53, v10
	v_add_f32_e32 v10, 1.0, v11
	v_add_f32_e32 v11, 1.0, v17
	v_add_f32_e32 v4, 1.0, v4
	v_add_f32_e32 v5, 1.0, v5
	v_rcp_f32_e32 v10, v10
	v_rcp_f32_e32 v11, v11
	v_rcp_f32_e32 v4, v4
	v_rcp_f32_e32 v5, v5
	v_mov_b32_e32 v15, s19
	v_sub_f32_e32 v15, s44, v15
	v_readlane_b32 s4, v154, s18
	v_readlane_b32 s5, v154, s16
	v_mul_f32_e32 v15, 0x3fb8aa3b, v15
	v_pk_mul_f32 v[8:9], v[18:19], v[10:11]
	v_pk_mul_f32 v[2:3], v[2:3], v[4:5]
	v_exp_f32_e32 v69, v15
	v_pk_mul_f32 v[8:9], v[8:9], s[4:5]
	v_pk_mul_f32 v[2:3], v[2:3], s[4:5]
	v_pk_mul_f32 v[4:5], v[12:13], s[4:5]
	v_pk_mul_f32 v[10:11], v[52:53], s[4:5]
	s_and_b32 s4, s18, 0x1fffffe2
	s_lshl_b32 s4, s4, 1
	s_lshl_b32 s5, s18, 2
	s_add_i32 s4, s38, s4
	s_and_b32 s5, s5, 48
	global_store_dword v[54:55], v65, off
	v_mov_b32_e32 v65, v16
	s_add_i32 s4, s4, s5
	v_pk_mul_f32 v[6:7], v[52:53], v[68:69]
	v_pk_mul_f32 v[10:11], v[10:11], v[64:65]
	s_add_i32 s4, s4, s17
	v_cvt_pk_bf16_f32 v2, v2, v3
	v_pk_mul_f32 v[4:5], v[4:5], v[64:65]
	v_cvt_pk_bf16_f32 v10, v10, v11
	ds_write_b32 v58, v2 offset:34828
	v_cvt_pk_bf16_f32 v2, v6, v7
	v_add_u32_e32 v3, s4, v88
	ds_write_b32 v58, v10 offset:53260
	ds_write_b32 v3, v2
	v_cvt_pk_bf16_f32 v2, v4, v5
	v_pk_mul_f32 v[14:15], v[12:13], v[68:69]
	ds_write_b32 v58, v2 offset:53404
	v_cvt_pk_bf16_f32 v2, v8, v9
	ds_write_b32 v58, v2 offset:34972
	v_cvt_pk_bf16_f32 v2, v14, v15
	v_add_u32_e32 v3, s4, v89
	s_bfe_u32 s19, s45, 0x20006
	v_and_b32_e32 v60, 48, v106
	ds_write_b32 v3, v2
	v_lshl_or_b32 v58, s19, 4, v144
	v_add_u32_e32 v2, 0, v60
	s_waitcnt lgkmcnt(0)
	s_barrier
	v_mad_u32_u24 v3, v58, s37, v2
	ds_read_b128 v[6:9], v3
	ds_read_b128 v[10:13], v3 offset:64
	ds_read_b128 v[14:17], v3 offset:128
	ds_read_b128 v[18:21], v3 offset:192
	s_lshr_b32 s18, s45, 8
	s_lshl_b32 s22, s18, 1
	s_cmp_ge_u32 s19, s22
	s_cselect_b64 s[4:5], -1, 0
	s_cmp_lt_u32 s19, s22
	v_lshl_or_b32 v3, s18, 5, v144
	s_cbranch_scc1 .LBB0_543
	v_mad_u64_u32 v[4:5], s[16:17], v3, s37, v[2:3]
	ds_read_b128 v[22:25], v4 offset:17408
	ds_read_b128 v[26:29], v4 offset:17472
	ds_read_b128 v[30:33], v4 offset:17536
	ds_read_b128 v[34:37], v4 offset:17600

.LBB0_1038:
	s_and_b64 vcc, exec, s[0:1]
	s_cbranch_vccz .LBB0_1083
	s_lshl_b32 s0, s84, 8
	s_and_b32 s14, s0, 0xfffff800
	s_lshl_b32 s8, s84, 5
	s_ashr_i32 s15, s14, 31
	s_mov_b64 s[38:39], s[28:29]
	s_and_b32 s28, s0, 0x700
	s_add_u32 s30, s68, s28
	s_addc_u32 s31, s69, 0
	s_add_u32 s34, s3, s28
	s_addc_u32 s35, s85, 0
	s_ashr_i32 s9, s8, 31
	s_lshl_b64 s[2:3], s[8:9], 14
	s_add_u32 s36, s38, s2
	s_addc_u32 s37, s39, s3
	s_add_u32 s10, s92, s28
	s_addc_u32 s11, s93, 0
	s_lshl_b64 s[0:1], s[8:9], 13
	s_add_u32 s0, s26, s0
	s_addc_u32 s1, s27, s1
	s_add_u32 s24, s66, s2
	s_addc_u32 s25, s67, s3
	s_lshl_b64 s[12:13], s[8:9], 2
	s_add_u32 s22, s78, s12
	s_addc_u32 s23, s79, s13
	s_or_b32 s2, s8, 1
	s_or_b32 s6, s14, 64
	s_ashr_i32 s3, s2, 31
	s_ashr_i32 s7, s6, 31
	s_lshl_b64 s[4:5], s[2:3], 14
	s_add_u32 s20, s38, s4
	s_addc_u32 s21, s39, s5
	s_lshl_b64 s[16:17], s[2:3], 13
	s_add_u32 s16, s26, s16
	s_addc_u32 s17, s27, s17
	s_add_u32 s18, s66, s4
	s_addc_u32 s19, s67, s5
	s_lshl_b64 s[2:3], s[2:3], 2
	s_add_u32 s4, s78, s2
	s_waitcnt vmcnt(10)
	v_mov_b32_e32 v46, v0
	v_readfirstlane_b32 s2, v0
	s_addc_u32 s5, s79, s3
	s_lshr_b32 s9, s2, 6
	v_lshlrev_b32_e32 v10, 3, v46
	v_ashrrev_i32_e32 v108, 4, v46
	v_and_b32_e32 v1, 15, v46
	s_lshl_b32 s2, s9, 4
	v_and_b32_e32 v47, 0x78, v10
	v_ashrrev_i32_e32 v109, 31, v108
	v_mov_b32_e32 v103, 0
	v_or_b32_e32 v2, s2, v1
	v_readlane_b32 s40, v245, 26
	v_lshlrev_b32_e32 v102, 1, v47
	v_lshl_add_u64 v[32:33], v[108:109], 0, s[14:15]
	s_waitcnt vmcnt(7)
	v_add_u32_e32 v49, 0x200, v46
	v_lshlrev_b32_e32 v2, 2, v2
	v_readlane_b32 s48, v245, 34
	v_readlane_b32 s49, v245, 35
	v_lshl_add_u64 v[104:105], s[30:31], 0, v[102:103]
	v_lshl_add_u64 v[106:107], s[34:35], 0, v[102:103]
	v_lshlrev_b64 v[34:35], 11, v[32:33]
	v_ashrrev_i32_e32 v112, 4, v49
	v_and_b32_e32 v48, 56, v10
	global_load_dword v128, v2, s[48:49]
	v_lshl_add_u64 v[2:3], v[104:105], 0, v[34:35]
	v_lshl_add_u64 v[6:7], v[106:107], 0, v[34:35]
	v_and_b32_e32 v110, 0xffffffc0, v10
	v_ashrrev_i32_e32 v113, 31, v112
	s_barrier
	v_lshlrev_b32_e32 v30, 1, v48
	v_mov_b32_e32 v31, v103
	global_load_dwordx4 v[2:5], v[2:3], off nt
	s_nop 0
	global_load_dwordx4 v[6:9], v[6:7], off nt
	v_ashrrev_i32_e32 v111, 31, v110
	v_lshl_add_u64 v[38:39], v[112:113], 0, s[14:15]
	v_lshl_add_u64 v[22:23], s[36:37], 0, v[30:31]
	v_lshlrev_b64 v[36:37], 1, v[110:111]
	v_lshlrev_b64 v[40:41], 11, v[38:39]
	v_lshl_add_u64 v[10:11], v[22:23], 0, v[36:37]
	v_lshl_add_u64 v[14:15], v[104:105], 0, v[40:41]
	v_lshl_add_u64 v[18:19], v[106:107], 0, v[40:41]
	v_lshlrev_b32_e32 v24, 3, v49
	v_ashrrev_i32_e32 v50, 3, v46
	global_load_dwordx4 v[10:13], v[10:11], off nt
	s_nop 0
	global_load_dwordx4 v[14:17], v[14:15], off nt
	s_nop 0
	global_load_dwordx4 v[18:21], v[18:19], off nt
	v_and_b32_e32 v114, 0xffffffc0, v24
	v_lshlrev_b32_e32 v26, 6, v50
	v_ashrrev_i32_e32 v115, 31, v114
	v_ashrrev_i32_e32 v27, 31, v26
	v_lshlrev_b64 v[42:43], 1, v[114:115]
	v_lshlrev_b64 v[44:45], 1, v[26:27]
	v_lshl_add_u64 v[22:23], v[22:23], 0, v[42:43]
	v_lshl_add_u64 v[26:27], s[0:1], 0, v[44:45]
	global_load_dwordx4 v[22:25], v[22:23], off nt
	v_lshl_add_u64 v[26:27], v[26:27], 0, v[30:31]
	global_load_dwordx4 v[26:29], v[26:27], off nt
	v_lshl_add_u64 v[116:117], s[10:11], 0, v[102:103]
	v_lshl_add_u64 v[34:35], v[116:117], 0, v[34:35]
	v_and_b32_e32 v51, 63, v46
	global_load_dwordx4 v[66:69], v[34:35], off nt
	v_lshl_add_u64 v[34:35], v[116:117], 0, v[40:41]
	s_lshl_b32 s10, s9, 9
	global_load_dwordx4 v[62:65], v[34:35], off nt
	v_lshlrev_b32_e32 v34, 2, v51
	v_mov_b32_e32 v35, v103
	s_ashr_i32 s11, s10, 31
	v_lshl_add_u64 v[40:41], s[24:25], 0, v[34:35]
	s_lshl_b64 s[24:25], s[10:11], 2
	v_lshl_add_u64 v[40:41], v[40:41], 0, s[24:25]
	s_movk_i32 s0, 0x88
	global_load_dword v156, v[40:41], off nt
	global_load_dword v157, v[40:41], off offset:256 nt
	global_load_dword v145, v[40:41], off offset:512 nt
	global_load_dword v147, v[40:41], off offset:768 nt
	global_load_dword v152, v[40:41], off offset:1024 nt
	global_load_dword v153, v[40:41], off offset:1280 nt
	global_load_dword v154, v[40:41], off offset:1536 nt
	global_load_dword v155, v[40:41], off offset:1792 nt
	global_load_dword v129, v103, s[22:23]
	v_mul_lo_u32 v40, v108, s0
	v_add_lshl_u32 v130, v40, v47, 1
	v_add_u32_e32 v40, 0, v130
	s_movk_i32 s3, 0x48
	s_waitcnt vmcnt(17)
	ds_write_b128 v40, v[2:5]
	s_waitcnt vmcnt(16)
	ds_write_b128 v40, v[6:9] offset:17408
	v_mul_lo_u32 v2, v50, s3
	v_mul_lo_u32 v3, v112, s0
	v_add_lshl_u32 v131, v2, v48, 1
	v_add_lshl_u32 v132, v3, v47, 1
	v_add_u32_e32 v2, 0, v131
	v_add_u32_e32 v3, 0, v132
	s_lshl_b32 s0, s9, 8
	v_lshrrev_b32_e32 v40, 1, v46
	s_add_i32 s15, 0, 0x1f100
	v_add_u32_e32 v41, s15, v102
	s_waitcnt vmcnt(15)
	ds_write_b128 v2, v[10:13] offset:44032
	s_waitcnt vmcnt(14)
	ds_write_b128 v3, v[14:17]
	s_waitcnt vmcnt(13)
	ds_write_b128 v3, v[18:21] offset:17408
	v_lshrrev_b32_e32 v3, 3, v49
	v_mul_lo_u32 v3, v3, s3
	v_add_lshl_u32 v133, v3, v48, 1
	v_add_u32_e32 v3, 0, v133
	s_waitcnt vmcnt(12)
	ds_write_b128 v3, v[22:25] offset:44032
	s_waitcnt vmcnt(11)
	ds_write_b128 v2, v[26:29] offset:34816
	v_lshl_add_u64 v[2:3], v[108:109], 0, s[6:7]
	v_lshlrev_b64 v[14:15], 11, v[2:3]
	v_lshl_add_u64 v[2:3], v[104:105], 0, v[14:15]
	v_lshl_add_u64 v[6:7], v[106:107], 0, v[14:15]
	v_lshl_add_u64 v[14:15], v[116:117], 0, v[14:15]
	s_waitcnt lgkmcnt(0)
	s_barrier
	global_load_dwordx4 v[2:5], v[2:3], off nt
	s_nop 0
	global_load_dwordx4 v[6:9], v[6:7], off nt
	v_lshl_add_u64 v[22:23], s[20:21], 0, v[30:31]
	global_load_dwordx4 v[238:241], v[14:15], off nt
	v_lshl_add_u64 v[14:15], v[112:113], 0, s[6:7]
	v_lshlrev_b64 v[26:27], 11, v[14:15]
	v_lshl_add_u64 v[10:11], v[22:23], 0, v[36:37]
	v_lshl_add_u64 v[14:15], v[104:105], 0, v[26:27]
	v_lshl_add_u64 v[18:19], v[106:107], 0, v[26:27]
	v_lshl_add_u64 v[26:27], v[116:117], 0, v[26:27]
	global_load_dwordx4 v[10:13], v[10:11], off nt
	s_nop 0
	global_load_dwordx4 v[14:17], v[14:15], off nt
	s_nop 0
	global_load_dwordx4 v[18:21], v[18:19], off nt
	v_lshl_add_u64 v[22:23], v[22:23], 0, v[42:43]
	global_load_dwordx4 v[246:249], v[26:27], off nt
	v_lshl_add_u64 v[26:27], s[16:17], 0, v[44:45]
	v_lshl_add_u64 v[26:27], v[26:27], 0, v[30:31]
	v_lshl_add_u64 v[28:29], s[18:19], 0, v[34:35]
	global_load_dwordx4 v[22:25], v[22:23], off nt
	v_lshl_add_u64 v[36:37], v[28:29], 0, s[24:25]
	global_load_dwordx4 v[26:29], v[26:27], off nt
	s_nop 0
	global_load_dword v230, v[36:37], off nt
	global_load_dword v231, v[36:37], off offset:256 nt
	global_load_dword v232, v[36:37], off offset:512 nt
	global_load_dword v233, v[36:37], off offset:768 nt
	global_load_dword v234, v[36:37], off offset:1024 nt
	global_load_dword v235, v[36:37], off offset:1280 nt
	global_load_dword v236, v[36:37], off offset:1536 nt
	global_load_dword v237, v[36:37], off offset:1792 nt
	global_load_dword v250, v103, s[4:5]
	s_add_i32 s6, 0, 0x1e800
	s_add_i32 s3, s6, s0
	v_and_b32_e32 v36, 7, v46
	s_lshl_b32 s0, s9, 5
	v_lshlrev_b32_e32 v37, 8, v36
	v_and_or_b32 v40, v40, 28, s0
	v_add3_u32 v136, s6, v37, v40
	v_cmp_eq_u32_e64 s[6:7], 0, v36
	s_add_i32 s9, 0, 0x1f000
	v_lshrrev_b32_e32 v36, 2, v46
	s_add_i32 s0, s15, s0
	v_add_u32_e32 v137, s9, v40
	v_and_b32_e32 v134, 12, v36
	v_lshl_add_u32 v40, v1, 1, s0
	s_movk_i32 s0, 0x110
	v_mov_b32_e32 v36, 0x1100
	v_mad_u32_u24 v138, v1, s0, v36
	s_movk_i32 s15, 0x90
	v_mov_b32_e32 v36, 0x900
	v_mad_u32_u24 v140, v1, s15, v36
	v_lshl_add_u32 v141, v134, 2, s9
	v_lshl_add_u64 v[36:37], s[26:27], 0, v[44:45]
	s_add_u32 s9, s94, s12
	v_lshl_add_u64 v[118:119], s[38:39], 0, v[30:31]
	v_lshl_add_u64 v[120:121], v[36:37], 0, v[30:31]
	v_lshl_add_u64 v[122:123], s[66:67], 0, v[34:35]
	s_addc_u32 s13, s95, s13
	v_lshlrev_b64 v[30:31], 12, v[38:39]
	v_lshlrev_b32_e32 v34, 4, v1
	s_add_u32 s12, s9, 0x130008
	v_or3_b32 v30, v30, s28, v34
	s_addc_u32 s13, s13, 0
	s_or_b32 s20, s8, 2
	v_lshl_add_u64 v[30:31], s[94:95], 0, v[30:31]
	s_mov_b64 s[8:9], 0x6b00000
	v_lshl_add_u64 v[124:125], v[30:31], 0, s[8:9]
	v_lshlrev_b64 v[30:31], 12, v[32:33]
	v_or3_b32 v30, v30, s28, v34
	s_mov_b32 s1, 0
	v_and_b32_e32 v135, 48, v46
	v_mul_u32_u24_e32 v42, 0x110, v134
	v_mul_lo_u32 v43, v108, s0
	v_mul_lo_u32 v46, v112, s0
	v_lshl_add_u64 v[30:31], s[94:95], 0, v[30:31]
	v_cmp_eq_u32_e64 s[4:5], 0, v1
	v_mul_u32_u24_e32 v102, 0x110, v1
	v_mul_u32_u24_e32 v139, 0x90, v1
	v_add_u32_e32 v142, 64, v141
	v_add_u32_e32 v143, 0x80, v141
	v_add_u32_e32 v144, 0xc0, v141
	s_mov_b32 s0, s10
	s_bitset1_b32 s14, 7
	v_lshl_add_u64 v[126:127], v[30:31], 0, s[8:9]
	v_mov_b32_e32 v146, 0x358637bd
	v_mov_b32_e32 v148, 0x260
	v_add_u32_e32 v149, v40, v42
	v_add_u32_e32 v150, v41, v43
	v_add_u32_e32 v151, v41, v46
	s_mov_b64 s[16:17], 0x40000
	s_mov_b32 s15, s1
	v_mov_b32_e32 v54, 0
	v_mov_b32_e32 v55, v103
	v_mov_b32_e32 v56, v103
	v_mov_b32_e32 v57, v103
	v_mov_b32_e32 v58, 0
	v_mov_b32_e32 v59, v103
	v_mov_b32_e32 v60, v103
	v_mov_b32_e32 v61, v103
	v_mov_b32_e32 v50, 0
	v_mov_b32_e32 v51, v103
	v_mov_b32_e32 v52, v103
	v_mov_b32_e32 v53, v103
	v_mov_b32_e32 v46, 0
	v_mov_b32_e32 v47, v103
	v_mov_b32_e32 v48, v103
	v_mov_b32_e32 v49, v103
	v_mov_b32_e32 v42, 0
	v_mov_b32_e32 v43, v103
	v_mov_b32_e32 v44, v103
	v_mov_b32_e32 v45, v103
	v_mov_b32_e32 v38, 0
	v_mov_b32_e32 v39, v103
	v_mov_b32_e32 v40, v103
	v_mov_b32_e32 v41, v103
	v_mov_b32_e32 v30, 0
	v_mov_b32_e32 v31, v103
	v_mov_b32_e32 v32, v103
	v_mov_b32_e32 v33, v103
	v_mov_b32_e32 v34, 0
	v_mov_b32_e32 v36, v103
	v_mov_b32_e32 v37, v103
	v_readlane_b32 s41, v245, 27
	v_readlane_b32 s42, v245, 28
	v_readlane_b32 s43, v245, 29
	v_readlane_b32 s44, v245, 30
	v_readlane_b32 s45, v245, 31
	v_readlane_b32 s46, v245, 32
	v_readlane_b32 s47, v245, 33
	v_readlane_b32 s50, v245, 36
	v_readlane_b32 s51, v245, 37
	v_readlane_b32 s52, v245, 38
	v_readlane_b32 s53, v245, 39
	v_readlane_b32 s54, v245, 40
	v_readlane_b32 s55, v245, 41
	s_waitcnt vmcnt(18)
	s_mov_b32 s98, 0xaaaaaaaa
	s_mov_b32 s99, 0xaaaaaaaa
	s_mov_b32 s100, 0xcccccccc
	s_mov_b32 s101, 0xcccccccc
	v_mbcnt_lo_u32_b32 v251, -1, 0
	v_mbcnt_hi_u32_b32 v251, -1, v251
	v_and_b32_e32 v252, 12, v251
	v_lshlrev_b32_e32 v252, 4, v252
	v_and_b32_e32 v251, 3, v251
	v_lshl_add_u32 v251, v251, 2, v252
	v_readfirstlane_b32 s8, v0
	s_nop 3
	s_lshr_b32 s8, s8, 6
	s_cmp_ge_u32 s8, 4
	s_cbranch_scc0 .Lscan_noprio
	s_setprio 1
.Lscan_noprio:
	s_branch .LBB0_1041

.LBB0_1079:
	s_setprio 0
	s_ashr_i32 s85, s84, 31
	s_lshl_b64 s[0:1], s[84:85], 16
	s_lshl_b32 s2, s2, 2
	s_add_u32 s2, s92, s2
	s_addc_u32 s3, s93, 0
	s_waitcnt vmcnt(15)
	v_lshlrev_b32_e32 v2, 2, v1
	v_mov_b32_e32 v3, 0
	v_lshl_add_u64 v[4:5], s[2:3], 0, v[2:3]
	v_lshlrev_b32_e32 v2, 9, v134
	v_lshl_add_u64 v[4:5], v[4:5], 0, s[0:1]
	v_lshl_add_u64 v[2:3], v[4:5], 0, v[2:3]
	s_mov_b64 s[0:1], 0x4400000
	v_lshl_add_u64 v[4:5], v[2:3], 0, s[0:1]
	s_mov_b32 s0, 0x4400000
	s_waitcnt vmcnt(14)
	v_add_co_u32_e32 v6, vcc, s0, v2
	s_mov_b32 s0, 0x4402000
	s_nop 0
	v_addc_co_u32_e32 v7, vcc, 0, v3, vcc
	global_store_dword v[6:7], v58, off
	global_store_dword v[4:5], v59, off offset:512
	global_store_dword v[4:5], v60, off offset:1024
	global_store_dword v[4:5], v61, off offset:1536
	v_add_co_u32_e32 v4, vcc, s0, v2
	s_mov_b32 s0, 0x4404000
	s_nop 0
	v_addc_co_u32_e32 v5, vcc, 0, v3, vcc
	global_store_dword v[4:5], v54, off
	global_store_dword v[4:5], v55, off offset:512
	global_store_dword v[4:5], v56, off offset:1024
	global_store_dword v[4:5], v57, off offset:1536
	v_add_co_u32_e32 v4, vcc, s0, v2
	s_mov_b32 s0, 0x4406000
	s_nop 0
	v_addc_co_u32_e32 v5, vcc, 0, v3, vcc
	global_store_dword v[4:5], v50, off
	global_store_dword v[4:5], v51, off offset:512
	global_store_dword v[4:5], v52, off offset:1024
	global_store_dword v[4:5], v53, off offset:1536
	v_add_co_u32_e32 v4, vcc, s0, v2
	s_mov_b32 s0, 0x4408000
	s_nop 0
	v_addc_co_u32_e32 v5, vcc, 0, v3, vcc
	global_store_dword v[4:5], v46, off
	global_store_dword v[4:5], v47, off offset:512
	global_store_dword v[4:5], v48, off offset:1024
	global_store_dword v[4:5], v49, off offset:1536
	v_add_co_u32_e32 v4, vcc, s0, v2
	s_mov_b32 s0, 0x440a000
	s_nop 0
	v_addc_co_u32_e32 v5, vcc, 0, v3, vcc
	global_store_dword v[4:5], v42, off
	global_store_dword v[4:5], v43, off offset:512
	global_store_dword v[4:5], v44, off offset:1024
	global_store_dword v[4:5], v45, off offset:1536
	v_add_co_u32_e32 v4, vcc, s0, v2
	s_mov_b32 s0, 0x440c000
	s_nop 0
	v_addc_co_u32_e32 v5, vcc, 0, v3, vcc
	global_store_dword v[4:5], v38, off
	global_store_dword v[4:5], v39, off offset:512
	global_store_dword v[4:5], v40, off offset:1024
	global_store_dword v[4:5], v41, off offset:1536
	v_add_co_u32_e32 v4, vcc, s0, v2
	s_nop 1
	v_addc_co_u32_e32 v5, vcc, 0, v3, vcc
	v_add_co_u32_e32 v2, vcc, 0x440e000, v2
	global_store_dword v[4:5], v30, off
	global_store_dword v[4:5], v31, off offset:512
	global_store_dword v[4:5], v32, off offset:1024
	global_store_dword v[4:5], v33, off offset:1536
	v_addc_co_u32_e32 v3, vcc, 0, v3, vcc
	global_store_dword v[2:3], v34, off
	global_store_dword v[2:3], v35, off offset:512
	global_store_dword v[2:3], v36, off offset:1024
	global_store_dword v[2:3], v37, off offset:1536
	s_waitcnt vmcnt(0)
	s_barrier
	s_mov_b64 s[0:1], exec
	v_readlane_b32 s2, v245, 4
	v_readlane_b32 s3, v245, 5
	s_and_b64 s[2:3], s[0:1], s[2:3]
	s_mov_b64 exec, s[2:3]
	s_cbranch_execz .LBB0_1082
	s_mov_b64 s[4:5], exec
	v_mbcnt_lo_u32_b32 v1, s4, 0
	buffer_wbl2 sc1
	s_waitcnt vmcnt(0)
	s_waitcnt vmcnt(0)
	v_mbcnt_hi_u32_b32 v1, s5, v1
	v_cmp_eq_u32_e32 vcc, 0, v1
	s_and_b64 s[2:3], exec, vcc
	s_mov_b64 exec, s[2:3]
	s_cbranch_execz .LBB0_1082
	s_bcnt1_i32_b64 s2, s[4:5]
	v_mov_b32_e32 v2, s2
	v_readlane_b32 s2, v245, 22
	v_mov_b32_e32 v1, 0
	v_readlane_b32 s3, v245, 23
	s_nop 4
	global_atomic_add v1, v2, s[2:3] offset:3600
